# GEMM phases: s_setprio 1 issued before the opening barrier (compute segment starts with an MFMA); O-proj epilogue: mid-epilogue store drain dropped
# baseline (speedup 1.0000x reference)
.LBB0_95:
	v_add_u32_e32 v0, 0x10000, v134
	ds_read_b128 v[136:139], v0
	ds_read_b128 v[140:143], v0 offset:1024
	ds_read_b128 v[144:147], v0 offset:2048
	ds_read_b128 v[148:151], v0 offset:3072
	v_add_u32_e32 v0, 0x14000, v134
	ds_read_b128 v[152:155], v0
	ds_read_b128 v[156:159], v0 offset:1024
	ds_read_b128 v[160:163], v0 offset:2048
	ds_read_b128 v[164:167], v0 offset:3072
	s_cmp_eq_u32 s51, 12
	s_cselect_b32 s56, s48, s26
	s_cselect_b32 s57, s49, s27
	s_cselect_b32 s54, s40, s24
	s_cselect_b32 s55, s41, s25
	s_add_u32 s52, s56, 0x80
	s_addc_u32 s53, s57, 0
	ds_read_b128 v[168:171], v135
	ds_read_b128 v[172:175], v135 offset:1024
	ds_read_b128 v[176:179], v135 offset:2048
	ds_read_b128 v[180:183], v135 offset:3072
	ds_read_b128 v[184:187], v135 offset:4096
	ds_read_b128 v[188:191], v135 offset:5120
	ds_read_b128 v[192:195], v135 offset:6144
	ds_read_b128 v[196:199], v135 offset:7168
	s_add_u32 s58, s26, s4
	s_addc_u32 s59, s27, s5
	s_add_u32 s58, s58, 0xffffff80
	s_addc_u32 s59, s59, -1
	s_mov_b32 m0, s71
	s_nop 0
	global_load_lds_dwordx4 v130, s[58:59]
	s_mov_b32 m0, s72
	s_nop 0
	global_load_lds_dwordx4 v132, s[58:59]
	s_waitcnt vmcnt(8) lgkmcnt(0)
	s_setprio 1
	s_barrier
	v_mfma_f32_16x16x32_bf16 v[126:129], v[136:139], v[168:171], v[126:129]
	v_mfma_f32_16x16x32_bf16 v[122:125], v[144:147], v[168:171], v[122:125]
	v_mfma_f32_16x16x32_bf16 v[110:113], v[136:139], v[176:179], v[110:113]
	v_mfma_f32_16x16x32_bf16 v[106:109], v[144:147], v[176:179], v[106:109]
	v_mfma_f32_16x16x32_bf16 v[94:97], v[136:139], v[184:187], v[94:97]
	v_mfma_f32_16x16x32_bf16 v[90:93], v[144:147], v[184:187], v[90:93]
	v_mfma_f32_16x16x32_bf16 v[78:81], v[136:139], v[192:195], v[78:81]
	v_mfma_f32_16x16x32_bf16 v[74:77], v[144:147], v[192:195], v[74:77]
	v_mfma_f32_16x16x32_bf16 v[126:129], v[140:143], v[172:175], v[126:129]
	v_mfma_f32_16x16x32_bf16 v[122:125], v[148:151], v[172:175], v[122:125]
	v_mfma_f32_16x16x32_bf16 v[110:113], v[140:143], v[180:183], v[110:113]
	v_mfma_f32_16x16x32_bf16 v[106:109], v[148:151], v[180:183], v[106:109]
	v_mfma_f32_16x16x32_bf16 v[94:97], v[140:143], v[188:191], v[94:97]
	v_mfma_f32_16x16x32_bf16 v[90:93], v[148:151], v[188:191], v[90:93]
	v_mfma_f32_16x16x32_bf16 v[78:81], v[140:143], v[196:199], v[78:81]
	v_mfma_f32_16x16x32_bf16 v[74:77], v[148:151], v[196:199], v[74:77]
	v_mfma_f32_16x16x32_bf16 v[118:121], v[152:155], v[168:171], v[118:121]
	v_mfma_f32_16x16x32_bf16 v[114:117], v[160:163], v[168:171], v[114:117]
	v_mfma_f32_16x16x32_bf16 v[102:105], v[152:155], v[176:179], v[102:105]
	v_mfma_f32_16x16x32_bf16 v[98:101], v[160:163], v[176:179], v[98:101]
	v_mfma_f32_16x16x32_bf16 v[86:89], v[152:155], v[184:187], v[86:89]
	v_mfma_f32_16x16x32_bf16 v[82:85], v[160:163], v[184:187], v[82:85]
	v_mfma_f32_16x16x32_bf16 v[70:73], v[152:155], v[192:195], v[70:73]
	v_mfma_f32_16x16x32_bf16 v[66:69], v[160:163], v[192:195], v[66:69]
	v_mfma_f32_16x16x32_bf16 v[118:121], v[156:159], v[172:175], v[118:121]
	v_mfma_f32_16x16x32_bf16 v[114:117], v[164:167], v[172:175], v[114:117]
	v_mfma_f32_16x16x32_bf16 v[102:105], v[156:159], v[180:183], v[102:105]
	v_mfma_f32_16x16x32_bf16 v[98:101], v[164:167], v[180:183], v[98:101]
	v_mfma_f32_16x16x32_bf16 v[86:89], v[156:159], v[188:191], v[86:89]
	v_mfma_f32_16x16x32_bf16 v[82:85], v[164:167], v[188:191], v[82:85]
	v_mfma_f32_16x16x32_bf16 v[70:73], v[156:159], v[196:199], v[70:73]
	v_mfma_f32_16x16x32_bf16 v[66:69], v[164:167], v[196:199], v[66:69]
	s_setprio 0
	s_barrier
	ds_read_b128 v[168:171], v135 offset:16384
	ds_read_b128 v[172:175], v135 offset:17408
	ds_read_b128 v[176:179], v135 offset:18432
	ds_read_b128 v[180:183], v135 offset:19456
	ds_read_b128 v[184:187], v135 offset:20480
	ds_read_b128 v[188:191], v135 offset:21504
	ds_read_b128 v[192:195], v135 offset:22528
	ds_read_b128 v[196:199], v135 offset:23552
	s_mov_b32 m0, s28
	s_nop 0
	global_load_lds_dwordx4 v131, s[54:55]
	s_mov_b32 m0, s29
	s_nop 0
	global_load_lds_dwordx4 v133, s[54:55]
	s_add_u32 s58, s54, s20
	s_addc_u32 s59, s55, s21
	s_mov_b32 m0, s30
	s_nop 0
	global_load_lds_dwordx4 v131, s[58:59]
	s_mov_b32 m0, s31
	s_nop 0
	global_load_lds_dwordx4 v133, s[58:59]
	s_nop 0
	s_mov_b32 m0, s11
	s_nop 0
	global_load_lds_dwordx4 v130, s[56:57]
	s_mov_b32 m0, s60
	s_nop 0
	global_load_lds_dwordx4 v132, s[56:57]
	s_waitcnt vmcnt(8) lgkmcnt(0)
	s_setprio 1
	s_barrier
	v_mfma_f32_16x16x32_bf16 v[62:65], v[136:139], v[168:171], v[62:65]
	v_mfma_f32_16x16x32_bf16 v[58:61], v[144:147], v[168:171], v[58:61]
	v_mfma_f32_16x16x32_bf16 v[46:49], v[136:139], v[176:179], v[46:49]
	v_mfma_f32_16x16x32_bf16 v[42:45], v[144:147], v[176:179], v[42:45]
	v_mfma_f32_16x16x32_bf16 v[30:33], v[136:139], v[184:187], v[30:33]
	v_mfma_f32_16x16x32_bf16 v[26:29], v[144:147], v[184:187], v[26:29]
	v_mfma_f32_16x16x32_bf16 v[14:17], v[136:139], v[192:195], v[14:17]
	v_mfma_f32_16x16x32_bf16 v[10:13], v[144:147], v[192:195], v[10:13]
	v_mfma_f32_16x16x32_bf16 v[62:65], v[140:143], v[172:175], v[62:65]
	v_mfma_f32_16x16x32_bf16 v[58:61], v[148:151], v[172:175], v[58:61]
	v_mfma_f32_16x16x32_bf16 v[46:49], v[140:143], v[180:183], v[46:49]
	v_mfma_f32_16x16x32_bf16 v[42:45], v[148:151], v[180:183], v[42:45]
	v_mfma_f32_16x16x32_bf16 v[30:33], v[140:143], v[188:191], v[30:33]
	v_mfma_f32_16x16x32_bf16 v[26:29], v[148:151], v[188:191], v[26:29]
	v_mfma_f32_16x16x32_bf16 v[14:17], v[140:143], v[196:199], v[14:17]
	v_mfma_f32_16x16x32_bf16 v[10:13], v[148:151], v[196:199], v[10:13]
	v_mfma_f32_16x16x32_bf16 v[54:57], v[152:155], v[168:171], v[54:57]
	v_mfma_f32_16x16x32_bf16 v[50:53], v[160:163], v[168:171], v[50:53]
	v_mfma_f32_16x16x32_bf16 v[38:41], v[152:155], v[176:179], v[38:41]
	v_mfma_f32_16x16x32_bf16 v[34:37], v[160:163], v[176:179], v[34:37]
	v_mfma_f32_16x16x32_bf16 v[22:25], v[152:155], v[184:187], v[22:25]
	v_mfma_f32_16x16x32_bf16 v[18:21], v[160:163], v[184:187], v[18:21]
	v_mfma_f32_16x16x32_bf16 v[6:9], v[152:155], v[192:195], v[6:9]
	v_mfma_f32_16x16x32_bf16 v[2:5], v[160:163], v[192:195], v[2:5]
	v_mfma_f32_16x16x32_bf16 v[54:57], v[156:159], v[172:175], v[54:57]
	v_mfma_f32_16x16x32_bf16 v[50:53], v[164:167], v[172:175], v[50:53]
	v_mfma_f32_16x16x32_bf16 v[38:41], v[156:159], v[180:183], v[38:41]
	v_mfma_f32_16x16x32_bf16 v[34:37], v[164:167], v[180:183], v[34:37]
	v_mfma_f32_16x16x32_bf16 v[22:25], v[156:159], v[188:191], v[22:25]
	v_mfma_f32_16x16x32_bf16 v[18:21], v[164:167], v[188:191], v[18:21]
	v_mfma_f32_16x16x32_bf16 v[6:9], v[156:159], v[196:199], v[6:9]
	v_mfma_f32_16x16x32_bf16 v[2:5], v[164:167], v[196:199], v[2:5]
	s_setprio 0
	s_barrier
	v_add_u32_e32 v0, 0x18000, v134
	ds_read_b128 v[136:139], v0
	ds_read_b128 v[140:143], v0 offset:1024
	ds_read_b128 v[144:147], v0 offset:2048
	ds_read_b128 v[148:151], v0 offset:3072
	v_add_u32_e32 v0, 0x1c000, v134
	ds_read_b128 v[152:155], v0
	ds_read_b128 v[156:159], v0 offset:1024
	ds_read_b128 v[160:163], v0 offset:2048
	ds_read_b128 v[164:167], v0 offset:3072
	ds_read_b128 v[168:171], v135 offset:32768
	ds_read_b128 v[172:175], v135 offset:33792
	ds_read_b128 v[176:179], v135 offset:34816
	ds_read_b128 v[180:183], v135 offset:35840
	ds_read_b128 v[184:187], v135 offset:36864
	ds_read_b128 v[188:191], v135 offset:37888
	ds_read_b128 v[192:195], v135 offset:38912
	ds_read_b128 v[196:199], v135 offset:39936
	s_add_u32 s56, s56, s4
	s_addc_u32 s57, s57, s5
	s_mov_b32 m0, s61
	s_nop 0
	global_load_lds_dwordx4 v130, s[56:57]
	s_mov_b32 m0, s62
	s_nop 0
	global_load_lds_dwordx4 v132, s[56:57]
	s_waitcnt vmcnt(8) lgkmcnt(0)
	s_setprio 1
	s_barrier
	v_mfma_f32_16x16x32_bf16 v[126:129], v[136:139], v[168:171], v[126:129]
	v_mfma_f32_16x16x32_bf16 v[122:125], v[144:147], v[168:171], v[122:125]
	v_mfma_f32_16x16x32_bf16 v[110:113], v[136:139], v[176:179], v[110:113]
	v_mfma_f32_16x16x32_bf16 v[106:109], v[144:147], v[176:179], v[106:109]
	v_mfma_f32_16x16x32_bf16 v[94:97], v[136:139], v[184:187], v[94:97]
	v_mfma_f32_16x16x32_bf16 v[90:93], v[144:147], v[184:187], v[90:93]
	v_mfma_f32_16x16x32_bf16 v[78:81], v[136:139], v[192:195], v[78:81]
	v_mfma_f32_16x16x32_bf16 v[74:77], v[144:147], v[192:195], v[74:77]
	v_mfma_f32_16x16x32_bf16 v[126:129], v[140:143], v[172:175], v[126:129]
	v_mfma_f32_16x16x32_bf16 v[122:125], v[148:151], v[172:175], v[122:125]
	v_mfma_f32_16x16x32_bf16 v[110:113], v[140:143], v[180:183], v[110:113]
	v_mfma_f32_16x16x32_bf16 v[106:109], v[148:151], v[180:183], v[106:109]
	v_mfma_f32_16x16x32_bf16 v[94:97], v[140:143], v[188:191], v[94:97]
	v_mfma_f32_16x16x32_bf16 v[90:93], v[148:151], v[188:191], v[90:93]
	v_mfma_f32_16x16x32_bf16 v[78:81], v[140:143], v[196:199], v[78:81]
	v_mfma_f32_16x16x32_bf16 v[74:77], v[148:151], v[196:199], v[74:77]
	v_mfma_f32_16x16x32_bf16 v[118:121], v[152:155], v[168:171], v[118:121]
	v_mfma_f32_16x16x32_bf16 v[114:117], v[160:163], v[168:171], v[114:117]
	v_mfma_f32_16x16x32_bf16 v[102:105], v[152:155], v[176:179], v[102:105]
	v_mfma_f32_16x16x32_bf16 v[98:101], v[160:163], v[176:179], v[98:101]
	v_mfma_f32_16x16x32_bf16 v[86:89], v[152:155], v[184:187], v[86:89]
	v_mfma_f32_16x16x32_bf16 v[82:85], v[160:163], v[184:187], v[82:85]
	v_mfma_f32_16x16x32_bf16 v[70:73], v[152:155], v[192:195], v[70:73]
	v_mfma_f32_16x16x32_bf16 v[66:69], v[160:163], v[192:195], v[66:69]
	v_mfma_f32_16x16x32_bf16 v[118:121], v[156:159], v[172:175], v[118:121]
	v_mfma_f32_16x16x32_bf16 v[114:117], v[164:167], v[172:175], v[114:117]
	v_mfma_f32_16x16x32_bf16 v[102:105], v[156:159], v[180:183], v[102:105]
	v_mfma_f32_16x16x32_bf16 v[98:101], v[164:167], v[180:183], v[98:101]
	v_mfma_f32_16x16x32_bf16 v[86:89], v[156:159], v[188:191], v[86:89]
	v_mfma_f32_16x16x32_bf16 v[82:85], v[164:167], v[188:191], v[82:85]
	v_mfma_f32_16x16x32_bf16 v[70:73], v[156:159], v[196:199], v[70:73]
	v_mfma_f32_16x16x32_bf16 v[66:69], v[164:167], v[196:199], v[66:69]
	s_setprio 0
	s_barrier
	ds_read_b128 v[168:171], v135 offset:49152
	ds_read_b128 v[172:175], v135 offset:50176
	ds_read_b128 v[176:179], v135 offset:51200
	ds_read_b128 v[180:183], v135 offset:52224
	ds_read_b128 v[184:187], v135 offset:53248
	ds_read_b128 v[188:191], v135 offset:54272
	ds_read_b128 v[192:195], v135 offset:55296
	ds_read_b128 v[196:199], v135 offset:56320
	s_add_u32 s54, s54, 0x80
	s_addc_u32 s55, s55, 0
	s_mov_b32 m0, s65
	s_nop 0
	global_load_lds_dwordx4 v131, s[54:55]
	s_mov_b32 m0, s66
	s_nop 0
	global_load_lds_dwordx4 v133, s[54:55]
	s_add_u32 s54, s58, 0x80
	s_addc_u32 s55, s59, 0
	s_mov_b32 m0, s69
	s_nop 0
	global_load_lds_dwordx4 v131, s[54:55]
	s_mov_b32 m0, s70
	s_nop 0
	global_load_lds_dwordx4 v133, s[54:55]
	s_mov_b32 m0, s67
	s_nop 0
	global_load_lds_dwordx4 v130, s[52:53]
	s_mov_b32 m0, s68
	s_nop 0
	global_load_lds_dwordx4 v132, s[52:53]
	s_waitcnt vmcnt(8) lgkmcnt(0)
	s_setprio 1
	s_barrier
	v_mfma_f32_16x16x32_bf16 v[62:65], v[136:139], v[168:171], v[62:65]
	v_mfma_f32_16x16x32_bf16 v[58:61], v[144:147], v[168:171], v[58:61]
	v_mfma_f32_16x16x32_bf16 v[46:49], v[136:139], v[176:179], v[46:49]
	v_mfma_f32_16x16x32_bf16 v[42:45], v[144:147], v[176:179], v[42:45]
	v_mfma_f32_16x16x32_bf16 v[30:33], v[136:139], v[184:187], v[30:33]
	v_mfma_f32_16x16x32_bf16 v[26:29], v[144:147], v[184:187], v[26:29]
	v_mfma_f32_16x16x32_bf16 v[14:17], v[136:139], v[192:195], v[14:17]
	v_mfma_f32_16x16x32_bf16 v[10:13], v[144:147], v[192:195], v[10:13]
	v_mfma_f32_16x16x32_bf16 v[62:65], v[140:143], v[172:175], v[62:65]
	v_mfma_f32_16x16x32_bf16 v[58:61], v[148:151], v[172:175], v[58:61]
	v_mfma_f32_16x16x32_bf16 v[46:49], v[140:143], v[180:183], v[46:49]
	v_mfma_f32_16x16x32_bf16 v[42:45], v[148:151], v[180:183], v[42:45]
	v_mfma_f32_16x16x32_bf16 v[30:33], v[140:143], v[188:191], v[30:33]
	v_mfma_f32_16x16x32_bf16 v[26:29], v[148:151], v[188:191], v[26:29]
	v_mfma_f32_16x16x32_bf16 v[14:17], v[140:143], v[196:199], v[14:17]
	v_mfma_f32_16x16x32_bf16 v[10:13], v[148:151], v[196:199], v[10:13]
	v_mfma_f32_16x16x32_bf16 v[54:57], v[152:155], v[168:171], v[54:57]
	v_mfma_f32_16x16x32_bf16 v[50:53], v[160:163], v[168:171], v[50:53]
	v_mfma_f32_16x16x32_bf16 v[38:41], v[152:155], v[176:179], v[38:41]
	v_mfma_f32_16x16x32_bf16 v[34:37], v[160:163], v[176:179], v[34:37]
	v_mfma_f32_16x16x32_bf16 v[22:25], v[152:155], v[184:187], v[22:25]
	v_mfma_f32_16x16x32_bf16 v[18:21], v[160:163], v[184:187], v[18:21]
	v_mfma_f32_16x16x32_bf16 v[6:9], v[152:155], v[192:195], v[6:9]
	v_mfma_f32_16x16x32_bf16 v[2:5], v[160:163], v[192:195], v[2:5]
	v_mfma_f32_16x16x32_bf16 v[54:57], v[156:159], v[172:175], v[54:57]
	v_mfma_f32_16x16x32_bf16 v[50:53], v[164:167], v[172:175], v[50:53]
	v_mfma_f32_16x16x32_bf16 v[38:41], v[156:159], v[180:183], v[38:41]
	v_mfma_f32_16x16x32_bf16 v[34:37], v[164:167], v[180:183], v[34:37]
	v_mfma_f32_16x16x32_bf16 v[22:25], v[156:159], v[188:191], v[22:25]
	v_mfma_f32_16x16x32_bf16 v[18:21], v[164:167], v[188:191], v[18:21]
	v_mfma_f32_16x16x32_bf16 v[6:9], v[156:159], v[196:199], v[6:9]
	v_mfma_f32_16x16x32_bf16 v[2:5], v[164:167], v[196:199], v[2:5]
	s_setprio 0
	s_barrier
	s_add_i32 s51, s51, 2
	s_add_u32 s24, s24, 0x100
	s_addc_u32 s25, s25, 0
	s_add_u32 s26, s26, 0x100
	s_addc_u32 s27, s27, 0
	s_cmp_gt_u32 s51, 13
	s_cbranch_scc0 .LBB0_95
	s_and_b64 vcc, exec, s[46:47]
	s_cbranch_vccz .LBB0_98
	s_barrier

.LBB0_122:
	s_add_u32 s56, s27, s54
	v_add_u32_e32 v0, 0x10000, v168
	s_addc_u32 s57, s53, s55
	ds_read_b128 v[130:133], v0
	ds_read_b128 v[134:137], v0 offset:1024
	ds_read_b128 v[138:141], v0 offset:2048
	ds_read_b128 v[142:145], v0 offset:3072
	v_add_u32_e32 v0, 0x14000, v168
	s_add_u32 s58, s48, s54
	ds_read_b128 v[146:149], v0
	ds_read_b128 v[150:153], v0 offset:1024
	ds_read_b128 v[154:157], v0 offset:2048
	ds_read_b128 v[158:161], v0 offset:3072
	s_addc_u32 s59, s49, s55
	s_add_u32 s58, s58, 0x100
	s_addc_u32 s59, s59, 0
	s_cmp_eq_u32 s91, 12
	s_cselect_b32 s60, s50, s56
	s_cselect_b32 s61, s51, s57
	s_cselect_b32 s58, s42, s58
	s_cselect_b32 s59, s43, s59
	s_add_u32 s56, s60, 0x80
	s_addc_u32 s57, s61, 0
	ds_read_b128 v[170:173], v169
	ds_read_b128 v[174:177], v169 offset:1024
	ds_read_b128 v[178:181], v169 offset:2048
	ds_read_b128 v[182:185], v169 offset:3072
	ds_read_b128 v[186:189], v169 offset:4096
	ds_read_b128 v[190:193], v169 offset:5120
	ds_read_b128 v[194:197], v169 offset:6144
	ds_read_b128 v[198:201], v169 offset:7168
	s_add_u32 s62, s76, s54
	s_addc_u32 s63, s90, s55
	s_mov_b32 m0, s85
	s_nop 0
	global_load_lds_dwordx4 v164, s[62:63]
	s_mov_b32 m0, s86
	s_nop 0
	global_load_lds_dwordx4 v166, s[62:63]
	s_waitcnt vmcnt(8) lgkmcnt(0)
	s_setprio 1
	s_barrier
	v_mfma_f32_16x16x32_bf16 v[126:129], v[130:133], v[170:173], v[126:129]
	v_mfma_f32_16x16x32_bf16 v[122:125], v[138:141], v[170:173], v[122:125]
	v_mfma_f32_16x16x32_bf16 v[118:121], v[130:133], v[178:181], v[118:121]
	v_mfma_f32_16x16x32_bf16 v[114:117], v[138:141], v[178:181], v[114:117]
	v_mfma_f32_16x16x32_bf16 v[110:113], v[130:133], v[186:189], v[110:113]
	v_mfma_f32_16x16x32_bf16 v[106:109], v[138:141], v[186:189], v[106:109]
	v_mfma_f32_16x16x32_bf16 v[102:105], v[130:133], v[194:197], v[102:105]
	v_mfma_f32_16x16x32_bf16 v[98:101], v[138:141], v[194:197], v[98:101]
	v_mfma_f32_16x16x32_bf16 v[126:129], v[134:137], v[174:177], v[126:129]
	v_mfma_f32_16x16x32_bf16 v[122:125], v[142:145], v[174:177], v[122:125]
	v_mfma_f32_16x16x32_bf16 v[118:121], v[134:137], v[182:185], v[118:121]
	v_mfma_f32_16x16x32_bf16 v[114:117], v[142:145], v[182:185], v[114:117]
	v_mfma_f32_16x16x32_bf16 v[110:113], v[134:137], v[190:193], v[110:113]
	v_mfma_f32_16x16x32_bf16 v[106:109], v[142:145], v[190:193], v[106:109]
	v_mfma_f32_16x16x32_bf16 v[102:105], v[134:137], v[198:201], v[102:105]
	v_mfma_f32_16x16x32_bf16 v[98:101], v[142:145], v[198:201], v[98:101]
	v_mfma_f32_16x16x32_bf16 v[94:97], v[146:149], v[170:173], v[94:97]
	v_mfma_f32_16x16x32_bf16 v[90:93], v[154:157], v[170:173], v[90:93]
	v_mfma_f32_16x16x32_bf16 v[86:89], v[146:149], v[178:181], v[86:89]
	v_mfma_f32_16x16x32_bf16 v[82:85], v[154:157], v[178:181], v[82:85]
	v_mfma_f32_16x16x32_bf16 v[78:81], v[146:149], v[186:189], v[78:81]
	v_mfma_f32_16x16x32_bf16 v[74:77], v[154:157], v[186:189], v[74:77]
	v_mfma_f32_16x16x32_bf16 v[70:73], v[146:149], v[194:197], v[70:73]
	v_mfma_f32_16x16x32_bf16 v[66:69], v[154:157], v[194:197], v[66:69]
	v_mfma_f32_16x16x32_bf16 v[94:97], v[150:153], v[174:177], v[94:97]
	v_mfma_f32_16x16x32_bf16 v[90:93], v[158:161], v[174:177], v[90:93]
	v_mfma_f32_16x16x32_bf16 v[86:89], v[150:153], v[182:185], v[86:89]
	v_mfma_f32_16x16x32_bf16 v[82:85], v[158:161], v[182:185], v[82:85]
	v_mfma_f32_16x16x32_bf16 v[78:81], v[150:153], v[190:193], v[78:81]
	v_mfma_f32_16x16x32_bf16 v[74:77], v[158:161], v[190:193], v[74:77]
	v_mfma_f32_16x16x32_bf16 v[70:73], v[150:153], v[198:201], v[70:73]
	v_mfma_f32_16x16x32_bf16 v[66:69], v[158:161], v[198:201], v[66:69]
	s_setprio 0
	s_barrier
	ds_read_b128 v[170:173], v169 offset:16384
	ds_read_b128 v[174:177], v169 offset:17408
	ds_read_b128 v[178:181], v169 offset:18432
	ds_read_b128 v[182:185], v169 offset:19456
	ds_read_b128 v[186:189], v169 offset:20480
	ds_read_b128 v[190:193], v169 offset:21504
	ds_read_b128 v[194:197], v169 offset:22528
	ds_read_b128 v[198:201], v169 offset:23552
	s_mov_b32 m0, s30
	s_nop 0
	global_load_lds_dwordx4 v165, s[58:59]
	s_mov_b32 m0, s31
	s_nop 0
	global_load_lds_dwordx4 v167, s[58:59]
	s_add_u32 s62, s58, s20
	s_addc_u32 s63, s59, s21
	s_mov_b32 m0, s64
	s_nop 0
	global_load_lds_dwordx4 v165, s[62:63]
	s_mov_b32 m0, s65
	s_nop 0
	global_load_lds_dwordx4 v167, s[62:63]
	s_nop 0
	s_mov_b32 m0, s29
	s_nop 0
	global_load_lds_dwordx4 v164, s[60:61]
	s_mov_b32 m0, s66
	s_nop 0
	global_load_lds_dwordx4 v166, s[60:61]
	s_waitcnt vmcnt(8) lgkmcnt(0)
	s_setprio 1
	s_barrier
	v_mfma_f32_16x16x32_bf16 v[62:65], v[130:133], v[170:173], v[62:65]
	v_mfma_f32_16x16x32_bf16 v[58:61], v[138:141], v[170:173], v[58:61]
	v_mfma_f32_16x16x32_bf16 v[54:57], v[130:133], v[178:181], v[54:57]
	v_mfma_f32_16x16x32_bf16 v[50:53], v[138:141], v[178:181], v[50:53]
	v_mfma_f32_16x16x32_bf16 v[46:49], v[130:133], v[186:189], v[46:49]
	v_mfma_f32_16x16x32_bf16 v[42:45], v[138:141], v[186:189], v[42:45]
	v_mfma_f32_16x16x32_bf16 v[38:41], v[130:133], v[194:197], v[38:41]
	v_mfma_f32_16x16x32_bf16 v[34:37], v[138:141], v[194:197], v[34:37]
	v_mfma_f32_16x16x32_bf16 v[62:65], v[134:137], v[174:177], v[62:65]
	v_mfma_f32_16x16x32_bf16 v[58:61], v[142:145], v[174:177], v[58:61]
	v_mfma_f32_16x16x32_bf16 v[54:57], v[134:137], v[182:185], v[54:57]
	v_mfma_f32_16x16x32_bf16 v[50:53], v[142:145], v[182:185], v[50:53]
	v_mfma_f32_16x16x32_bf16 v[46:49], v[134:137], v[190:193], v[46:49]
	v_mfma_f32_16x16x32_bf16 v[42:45], v[142:145], v[190:193], v[42:45]
	v_mfma_f32_16x16x32_bf16 v[38:41], v[134:137], v[198:201], v[38:41]
	v_mfma_f32_16x16x32_bf16 v[34:37], v[142:145], v[198:201], v[34:37]
	v_mfma_f32_16x16x32_bf16 v[30:33], v[146:149], v[170:173], v[30:33]
	v_mfma_f32_16x16x32_bf16 v[26:29], v[154:157], v[170:173], v[26:29]
	v_mfma_f32_16x16x32_bf16 v[22:25], v[146:149], v[178:181], v[22:25]
	v_mfma_f32_16x16x32_bf16 v[18:21], v[154:157], v[178:181], v[18:21]
	v_mfma_f32_16x16x32_bf16 v[14:17], v[146:149], v[186:189], v[14:17]
	v_mfma_f32_16x16x32_bf16 v[10:13], v[154:157], v[186:189], v[10:13]
	v_mfma_f32_16x16x32_bf16 v[6:9], v[146:149], v[194:197], v[6:9]
	v_mfma_f32_16x16x32_bf16 v[2:5], v[154:157], v[194:197], v[2:5]
	v_mfma_f32_16x16x32_bf16 v[30:33], v[150:153], v[174:177], v[30:33]
	v_mfma_f32_16x16x32_bf16 v[26:29], v[158:161], v[174:177], v[26:29]
	v_mfma_f32_16x16x32_bf16 v[22:25], v[150:153], v[182:185], v[22:25]
	v_mfma_f32_16x16x32_bf16 v[18:21], v[158:161], v[182:185], v[18:21]
	v_mfma_f32_16x16x32_bf16 v[14:17], v[150:153], v[190:193], v[14:17]
	v_mfma_f32_16x16x32_bf16 v[10:13], v[158:161], v[190:193], v[10:13]
	v_mfma_f32_16x16x32_bf16 v[6:9], v[150:153], v[198:201], v[6:9]
	v_mfma_f32_16x16x32_bf16 v[2:5], v[158:161], v[198:201], v[2:5]
	s_setprio 0
	s_barrier
	v_add_u32_e32 v0, 0x18000, v168
	ds_read_b128 v[130:133], v0
	ds_read_b128 v[134:137], v0 offset:1024
	ds_read_b128 v[138:141], v0 offset:2048
	ds_read_b128 v[142:145], v0 offset:3072
	v_add_u32_e32 v0, 0x1c000, v168
	ds_read_b128 v[146:149], v0
	ds_read_b128 v[150:153], v0 offset:1024
	ds_read_b128 v[154:157], v0 offset:2048
	ds_read_b128 v[158:161], v0 offset:3072
	ds_read_b128 v[170:173], v169 offset:32768
	ds_read_b128 v[174:177], v169 offset:33792
	ds_read_b128 v[178:181], v169 offset:34816
	ds_read_b128 v[182:185], v169 offset:35840
	ds_read_b128 v[186:189], v169 offset:36864
	ds_read_b128 v[190:193], v169 offset:37888
	ds_read_b128 v[194:197], v169 offset:38912
	ds_read_b128 v[198:201], v169 offset:39936
	s_add_u32 s60, s60, s4
	s_addc_u32 s61, s61, s5
	s_mov_b32 m0, s68
	s_nop 0
	global_load_lds_dwordx4 v164, s[60:61]
	s_mov_b32 m0, s69
	s_nop 0
	global_load_lds_dwordx4 v166, s[60:61]
	s_waitcnt vmcnt(8) lgkmcnt(0)
	s_setprio 1
	s_barrier
	v_mfma_f32_16x16x32_bf16 v[126:129], v[130:133], v[170:173], v[126:129]
	v_mfma_f32_16x16x32_bf16 v[122:125], v[138:141], v[170:173], v[122:125]
	v_mfma_f32_16x16x32_bf16 v[118:121], v[130:133], v[178:181], v[118:121]
	v_mfma_f32_16x16x32_bf16 v[114:117], v[138:141], v[178:181], v[114:117]
	v_mfma_f32_16x16x32_bf16 v[110:113], v[130:133], v[186:189], v[110:113]
	v_mfma_f32_16x16x32_bf16 v[106:109], v[138:141], v[186:189], v[106:109]
	v_mfma_f32_16x16x32_bf16 v[102:105], v[130:133], v[194:197], v[102:105]
	v_mfma_f32_16x16x32_bf16 v[98:101], v[138:141], v[194:197], v[98:101]
	v_mfma_f32_16x16x32_bf16 v[126:129], v[134:137], v[174:177], v[126:129]
	v_mfma_f32_16x16x32_bf16 v[122:125], v[142:145], v[174:177], v[122:125]
	v_mfma_f32_16x16x32_bf16 v[118:121], v[134:137], v[182:185], v[118:121]
	v_mfma_f32_16x16x32_bf16 v[114:117], v[142:145], v[182:185], v[114:117]
	v_mfma_f32_16x16x32_bf16 v[110:113], v[134:137], v[190:193], v[110:113]
	v_mfma_f32_16x16x32_bf16 v[106:109], v[142:145], v[190:193], v[106:109]
	v_mfma_f32_16x16x32_bf16 v[102:105], v[134:137], v[198:201], v[102:105]
	v_mfma_f32_16x16x32_bf16 v[98:101], v[142:145], v[198:201], v[98:101]
	v_mfma_f32_16x16x32_bf16 v[94:97], v[146:149], v[170:173], v[94:97]
	v_mfma_f32_16x16x32_bf16 v[90:93], v[154:157], v[170:173], v[90:93]
	v_mfma_f32_16x16x32_bf16 v[86:89], v[146:149], v[178:181], v[86:89]
	v_mfma_f32_16x16x32_bf16 v[82:85], v[154:157], v[178:181], v[82:85]
	v_mfma_f32_16x16x32_bf16 v[78:81], v[146:149], v[186:189], v[78:81]
	v_mfma_f32_16x16x32_bf16 v[74:77], v[154:157], v[186:189], v[74:77]
	v_mfma_f32_16x16x32_bf16 v[70:73], v[146:149], v[194:197], v[70:73]
	v_mfma_f32_16x16x32_bf16 v[66:69], v[154:157], v[194:197], v[66:69]
	v_mfma_f32_16x16x32_bf16 v[94:97], v[150:153], v[174:177], v[94:97]
	v_mfma_f32_16x16x32_bf16 v[90:93], v[158:161], v[174:177], v[90:93]
	v_mfma_f32_16x16x32_bf16 v[86:89], v[150:153], v[182:185], v[86:89]
	v_mfma_f32_16x16x32_bf16 v[82:85], v[158:161], v[182:185], v[82:85]
	v_mfma_f32_16x16x32_bf16 v[78:81], v[150:153], v[190:193], v[78:81]
	v_mfma_f32_16x16x32_bf16 v[74:77], v[158:161], v[190:193], v[74:77]
	v_mfma_f32_16x16x32_bf16 v[70:73], v[150:153], v[198:201], v[70:73]
	v_mfma_f32_16x16x32_bf16 v[66:69], v[158:161], v[198:201], v[66:69]
	s_setprio 0
	s_barrier
	ds_read_b128 v[170:173], v169 offset:49152
	ds_read_b128 v[174:177], v169 offset:50176
	ds_read_b128 v[178:181], v169 offset:51200
	ds_read_b128 v[182:185], v169 offset:52224
	ds_read_b128 v[186:189], v169 offset:53248
	ds_read_b128 v[190:193], v169 offset:54272
	ds_read_b128 v[194:197], v169 offset:55296
	ds_read_b128 v[198:201], v169 offset:56320
	s_add_u32 s58, s58, 0x80
	s_addc_u32 s59, s59, 0
	s_mov_b32 m0, s75
	s_nop 0
	global_load_lds_dwordx4 v165, s[58:59]
	s_mov_b32 m0, s80
	s_nop 0
	global_load_lds_dwordx4 v167, s[58:59]
	s_add_u32 s58, s62, 0x80
	s_addc_u32 s59, s63, 0
	s_mov_b32 m0, s83
	s_nop 0
	global_load_lds_dwordx4 v165, s[58:59]
	s_mov_b32 m0, s84
	s_nop 0
	global_load_lds_dwordx4 v167, s[58:59]
	s_mov_b32 m0, s81
	s_nop 0
	global_load_lds_dwordx4 v164, s[56:57]
	s_mov_b32 m0, s82
	s_nop 0
	global_load_lds_dwordx4 v166, s[56:57]
	s_waitcnt vmcnt(8) lgkmcnt(0)
	s_setprio 1
	s_barrier
	v_mfma_f32_16x16x32_bf16 v[62:65], v[130:133], v[170:173], v[62:65]
	v_mfma_f32_16x16x32_bf16 v[58:61], v[138:141], v[170:173], v[58:61]
	v_mfma_f32_16x16x32_bf16 v[54:57], v[130:133], v[178:181], v[54:57]
	v_mfma_f32_16x16x32_bf16 v[50:53], v[138:141], v[178:181], v[50:53]
	v_mfma_f32_16x16x32_bf16 v[46:49], v[130:133], v[186:189], v[46:49]
	v_mfma_f32_16x16x32_bf16 v[42:45], v[138:141], v[186:189], v[42:45]
	v_mfma_f32_16x16x32_bf16 v[38:41], v[130:133], v[194:197], v[38:41]
	v_mfma_f32_16x16x32_bf16 v[34:37], v[138:141], v[194:197], v[34:37]
	v_mfma_f32_16x16x32_bf16 v[62:65], v[134:137], v[174:177], v[62:65]
	v_mfma_f32_16x16x32_bf16 v[58:61], v[142:145], v[174:177], v[58:61]
	v_mfma_f32_16x16x32_bf16 v[54:57], v[134:137], v[182:185], v[54:57]
	v_mfma_f32_16x16x32_bf16 v[50:53], v[142:145], v[182:185], v[50:53]
	v_mfma_f32_16x16x32_bf16 v[46:49], v[134:137], v[190:193], v[46:49]
	v_mfma_f32_16x16x32_bf16 v[42:45], v[142:145], v[190:193], v[42:45]
	v_mfma_f32_16x16x32_bf16 v[38:41], v[134:137], v[198:201], v[38:41]
	v_mfma_f32_16x16x32_bf16 v[34:37], v[142:145], v[198:201], v[34:37]
	v_mfma_f32_16x16x32_bf16 v[30:33], v[146:149], v[170:173], v[30:33]
	v_mfma_f32_16x16x32_bf16 v[26:29], v[154:157], v[170:173], v[26:29]
	v_mfma_f32_16x16x32_bf16 v[22:25], v[146:149], v[178:181], v[22:25]
	v_mfma_f32_16x16x32_bf16 v[18:21], v[154:157], v[178:181], v[18:21]
	v_mfma_f32_16x16x32_bf16 v[14:17], v[146:149], v[186:189], v[14:17]
	v_mfma_f32_16x16x32_bf16 v[10:13], v[154:157], v[186:189], v[10:13]
	v_mfma_f32_16x16x32_bf16 v[6:9], v[146:149], v[194:197], v[6:9]
	v_mfma_f32_16x16x32_bf16 v[2:5], v[154:157], v[194:197], v[2:5]
	v_mfma_f32_16x16x32_bf16 v[30:33], v[150:153], v[174:177], v[30:33]
	v_mfma_f32_16x16x32_bf16 v[26:29], v[158:161], v[174:177], v[26:29]
	v_mfma_f32_16x16x32_bf16 v[22:25], v[150:153], v[182:185], v[22:25]
	v_mfma_f32_16x16x32_bf16 v[18:21], v[158:161], v[182:185], v[18:21]
	v_mfma_f32_16x16x32_bf16 v[14:17], v[150:153], v[190:193], v[14:17]
	v_mfma_f32_16x16x32_bf16 v[10:13], v[158:161], v[190:193], v[10:13]
	v_mfma_f32_16x16x32_bf16 v[6:9], v[150:153], v[198:201], v[6:9]
	v_mfma_f32_16x16x32_bf16 v[2:5], v[158:161], v[198:201], v[2:5]
	s_setprio 0
	s_barrier
	s_add_i32 s91, s91, 2
	s_add_u32 s54, s54, 0x100
	s_addc_u32 s55, s55, 0
	s_cmp_gt_u32 s91, 13
	s_cbranch_scc0 .LBB0_122
	s_and_b64 vcc, exec, s[46:47]
	s_cbranch_vccz .LBB0_125
	s_barrier
.LBB0_125:
	s_add_u32 s54, s27, 0xffffff00
	s_addc_u32 s55, s53, -1
	s_sub_i32 s27, s52, 32
	s_lshr_b32 s27, s27, 3
	s_mul_i32 s27, s27, 6
	s_add_i32 s27, s27, 8
	s_cmp_gt_i32 s52, 31
	s_cselect_b32 s56, s27, 2
	s_ashr_i32 s57, s56, 31
	s_lshl_b64 s[56:57], s[56:57], 12
	v_mov_b32_e32 v0, v249
	s_add_u32 s56, s72, s56
	s_addc_u32 s57, s73, s57
	s_lshl_b32 s27, s67, 8
	v_lshrrev_b32_e32 v130, 2, v0
	s_or_b32 s27, s27, s87
	v_and_b32_e32 v150, 12, v130
	v_or_b32_e32 v146, s27, v150
	v_ashrrev_i32_e32 v147, 31, v146
	s_ashr_i32 s53, s52, 31
	v_lshl_add_u64 v[130:131], v[146:147], 2, s[56:57]
	s_lshl_b64 s[56:57], s[52:53], 19
	s_add_u32 s56, s70, s56
	v_and_or_b32 v148, v0, 15, s74
	v_mov_b32_e32 v149, s88
	s_addc_u32 s57, s71, s57
	v_and_b32_e32 v0, 16, v0
	v_lshl_add_u64 v[146:147], v[146:147], 1, s[56:57]
	v_lshlrev_b64 v[148:149], 11, v[148:149]
	v_add_u32_e32 v151, 12, v150
	v_cmp_eq_u32_e32 vcc, 0, v0
	v_lshl_add_u64 v[146:147], v[146:147], 0, v[148:149]
	v_lshlrev_b32_e32 v148, 1, v150
	v_cndmask_b32_e32 v0, v151, v150, vcc
	v_sub_co_u32_e32 v146, vcc, v146, v148
	v_lshlrev_b32_e32 v0, 1, v0
	s_nop 0
	v_subbrev_co_u32_e32 v147, vcc, 0, v147, vcc
	v_lshl_add_u64 v[158:159], v[146:147], 0, v[0:1]
	s_mov_b32 s27, 0x8000
	v_add_co_u32_e32 v190, vcc, s27, v158
	s_mov_b32 s27, 0x10000
	s_nop 0
	v_addc_co_u32_e32 v191, vcc, 0, v159, vcc
	v_add_co_u32_e32 v162, vcc, s27, v158
	s_mov_b32 s27, 0x18000
	s_nop 0
	v_addc_co_u32_e32 v163, vcc, 0, v159, vcc
	flat_load_dwordx4 v[142:145], v[130:131]
	flat_load_dwordx4 v[138:141], v[130:131] offset:64
	flat_load_dwordx4 v[134:137], v[130:131] offset:128
	s_nop 0
	flat_load_dwordx4 v[130:133], v[130:131] offset:192
	v_add_co_u32_e32 v160, vcc, s27, v158
	flat_load_dwordx4 v[170:173], v[158:159]
	flat_load_dwordx4 v[174:177], v[158:159] offset:64
	v_addc_co_u32_e32 v161, vcc, 0, v159, vcc
	flat_load_dwordx4 v[178:181], v[190:191]
	flat_load_dwordx4 v[182:185], v[190:191] offset:64
	flat_load_dwordx4 v[186:189], v[162:163]
	flat_load_dwordx4 v[154:157], v[162:163] offset:64
	flat_load_dwordx4 v[150:153], v[160:161]
	flat_load_dwordx4 v[146:149], v[160:161] offset:64
	s_mov_b64 s[56:57], 0x40000
	v_lshl_add_u64 v[208:209], v[158:159], 0, s[56:57]
	flat_load_dwordx4 v[216:219], v[208:209]
	flat_load_dwordx4 v[220:223], v[208:209] offset:64
	s_mov_b64 s[56:57], 0x8000
	v_lshl_add_u64 v[208:209], v[208:209], 0, s[56:57]
	flat_load_dwordx4 v[224:227], v[208:209]
	flat_load_dwordx4 v[228:231], v[208:209] offset:64
	v_lshl_add_u64 v[208:209], v[208:209], 0, s[56:57]
	flat_load_dwordx4 v[232:235], v[208:209]
	flat_load_dwordx4 v[240:243], v[208:209] offset:64
	v_lshl_add_u64 v[208:209], v[208:209], 0, s[56:57]
	flat_load_dwordx4 v[244:247], v[208:209]
	flat_load_dwordx4 v[202:205], v[208:209] offset:64
	s_waitcnt vmcnt(0) lgkmcnt(0)
	v_mov_b32_e32 v0, v172
	v_mov_b32_e32 v172, v173
	s_nop 0
	v_permlane16_swap_b32_e32 v170, v0
	v_permlane16_swap_b32_e32 v171, v172
	v_mov_b32_e32 v194, v156
	v_mov_b32_e32 v195, v157
	v_mov_b32_e32 v196, v152
	v_mov_b32_e32 v197, v153
	v_mov_b32_e32 v198, v148
	v_mov_b32_e32 v199, v149
	v_lshlrev_b32_e32 v148, 16, v170
	v_and_b32_e32 v149, 0xffff0000, v170
	v_lshlrev_b32_e32 v152, 16, v171
	v_and_b32_e32 v153, 0xffff0000, v171
	v_lshlrev_b32_e32 v156, 16, v0
	v_and_b32_e32 v157, 0xffff0000, v0
	v_lshlrev_b32_e32 v170, 16, v172
	v_and_b32_e32 v171, 0xffff0000, v172
	v_mov_b32_e32 v192, v176
	v_mov_b32_e32 v193, v177
	v_pk_fma_f32 v[152:153], v[128:129], v[144:145], v[152:153]
	v_pk_fma_f32 v[148:149], v[126:127], v[142:143], v[148:149]
	v_pk_fma_f32 v[176:177], v[124:125], v[140:141], v[170:171]
	v_pk_fma_f32 v[156:157], v[122:123], v[138:139], v[156:157]
	v_cvt_pk_bf16_f32 v170, v148, v149
	v_cvt_pk_bf16_f32 v171, v152, v153
	v_cvt_pk_bf16_f32 v172, v156, v157
	v_cvt_pk_bf16_f32 v173, v176, v177
	v_permlane16_swap_b32_e32 v174, v192
	v_permlane16_swap_b32_e32 v175, v193
	v_permlane16_swap_b32_e32 v170, v172
	v_permlane16_swap_b32_e32 v171, v173
	flat_store_dwordx4 v[158:159], v[170:173]
	v_lshlrev_b32_e32 v148, 16, v174
	v_and_b32_e32 v149, 0xffff0000, v174
	v_lshlrev_b32_e32 v152, 16, v175
	v_and_b32_e32 v153, 0xffff0000, v175
	v_lshlrev_b32_e32 v156, 16, v192
	v_and_b32_e32 v157, 0xffff0000, v192
	v_lshlrev_b32_e32 v170, 16, v193
	v_and_b32_e32 v171, 0xffff0000, v193
	v_pk_fma_f32 v[152:153], v[96:97], v[136:137], v[152:153]
	v_pk_fma_f32 v[148:149], v[94:95], v[134:135], v[148:149]
	v_pk_fma_f32 v[174:175], v[92:93], v[132:133], v[170:171]
	v_pk_fma_f32 v[156:157], v[90:91], v[130:131], v[156:157]
	v_cvt_pk_bf16_f32 v170, v148, v149
	v_cvt_pk_bf16_f32 v171, v152, v153
	v_cvt_pk_bf16_f32 v172, v156, v157
	v_cvt_pk_bf16_f32 v173, v174, v175
	v_permlane16_swap_b32_e32 v178, v180
	v_permlane16_swap_b32_e32 v179, v181
	v_permlane16_swap_b32_e32 v170, v172
	v_permlane16_swap_b32_e32 v171, v173
	flat_store_dwordx4 v[158:159], v[170:173] offset:64
	v_lshlrev_b32_e32 v148, 16, v178
	v_and_b32_e32 v149, 0xffff0000, v178
	v_lshlrev_b32_e32 v152, 16, v179
	v_and_b32_e32 v153, 0xffff0000, v179
	v_lshlrev_b32_e32 v156, 16, v180
	v_and_b32_e32 v157, 0xffff0000, v180
	v_lshlrev_b32_e32 v170, 16, v181
	v_and_b32_e32 v171, 0xffff0000, v181
	v_pk_fma_f32 v[152:153], v[120:121], v[144:145], v[152:153]
	v_pk_fma_f32 v[148:149], v[118:119], v[142:143], v[148:149]
	v_pk_fma_f32 v[174:175], v[116:117], v[140:141], v[170:171]
	v_pk_fma_f32 v[156:157], v[114:115], v[138:139], v[156:157]
	v_cvt_pk_bf16_f32 v170, v148, v149
	v_cvt_pk_bf16_f32 v171, v152, v153
	v_cvt_pk_bf16_f32 v172, v156, v157
	v_cvt_pk_bf16_f32 v173, v174, v175
	v_permlane16_swap_b32_e32 v182, v184
	v_permlane16_swap_b32_e32 v183, v185
	v_permlane16_swap_b32_e32 v170, v172
	v_permlane16_swap_b32_e32 v171, v173
	flat_store_dwordx4 v[190:191], v[170:173]
	v_lshlrev_b32_e32 v148, 16, v182
	v_and_b32_e32 v149, 0xffff0000, v182
	v_lshlrev_b32_e32 v152, 16, v183
	v_and_b32_e32 v153, 0xffff0000, v183
	v_lshlrev_b32_e32 v156, 16, v184
	v_and_b32_e32 v157, 0xffff0000, v184
	v_lshlrev_b32_e32 v170, 16, v185
	v_and_b32_e32 v171, 0xffff0000, v185
	v_pk_fma_f32 v[152:153], v[88:89], v[136:137], v[152:153]
	v_pk_fma_f32 v[148:149], v[86:87], v[134:135], v[148:149]
	v_pk_fma_f32 v[174:175], v[84:85], v[132:133], v[170:171]
	v_pk_fma_f32 v[156:157], v[82:83], v[130:131], v[156:157]
	v_cvt_pk_bf16_f32 v170, v148, v149
	v_cvt_pk_bf16_f32 v171, v152, v153
	v_cvt_pk_bf16_f32 v172, v156, v157
	v_cvt_pk_bf16_f32 v173, v174, v175
	v_permlane16_swap_b32_e32 v186, v188
	v_permlane16_swap_b32_e32 v187, v189
	v_permlane16_swap_b32_e32 v170, v172
	v_permlane16_swap_b32_e32 v171, v173
	flat_store_dwordx4 v[190:191], v[170:173] offset:64
	v_lshlrev_b32_e32 v148, 16, v186
	v_and_b32_e32 v149, 0xffff0000, v186
	v_lshlrev_b32_e32 v152, 16, v187
	v_and_b32_e32 v153, 0xffff0000, v187
	v_lshlrev_b32_e32 v156, 16, v188
	v_and_b32_e32 v157, 0xffff0000, v188
	v_lshlrev_b32_e32 v170, 16, v189
	v_and_b32_e32 v171, 0xffff0000, v189
	v_permlane16_swap_b32_e32 v155, v195
	v_pk_fma_f32 v[152:153], v[112:113], v[144:145], v[152:153]
	v_pk_fma_f32 v[148:149], v[110:111], v[142:143], v[148:149]
	v_pk_fma_f32 v[174:175], v[108:109], v[140:141], v[170:171]
	v_pk_fma_f32 v[156:157], v[106:107], v[138:139], v[156:157]
	v_permlane16_swap_b32_e32 v154, v194
	v_cvt_pk_bf16_f32 v170, v148, v149
	v_cvt_pk_bf16_f32 v171, v152, v153
	v_cvt_pk_bf16_f32 v172, v156, v157
	v_cvt_pk_bf16_f32 v173, v174, v175
	v_lshlrev_b32_e32 v152, 16, v155
	v_and_b32_e32 v153, 0xffff0000, v155
	v_permlane16_swap_b32_e32 v170, v172
	v_permlane16_swap_b32_e32 v171, v173
	v_lshlrev_b32_e32 v148, 16, v154
	v_and_b32_e32 v149, 0xffff0000, v154
	v_pk_fma_f32 v[154:155], v[80:81], v[136:137], v[152:153]
	v_lshlrev_b32_e32 v152, 16, v194
	v_and_b32_e32 v153, 0xffff0000, v194
	v_lshlrev_b32_e32 v156, 16, v195
	v_and_b32_e32 v157, 0xffff0000, v195
	flat_store_dwordx4 v[162:163], v[170:173]
	v_pk_fma_f32 v[148:149], v[78:79], v[134:135], v[148:149]
	v_pk_fma_f32 v[156:157], v[76:77], v[132:133], v[156:157]
	v_pk_fma_f32 v[170:171], v[74:75], v[130:131], v[152:153]
	v_cvt_pk_bf16_f32 v152, v148, v149
	v_cvt_pk_bf16_f32 v153, v154, v155
	v_cvt_pk_bf16_f32 v154, v170, v171
	v_cvt_pk_bf16_f32 v155, v156, v157
	v_permlane16_swap_b32_e32 v150, v196
	v_permlane16_swap_b32_e32 v151, v197
	v_permlane16_swap_b32_e32 v152, v154
	v_permlane16_swap_b32_e32 v153, v155
	flat_store_dwordx4 v[162:163], v[152:155] offset:64
	v_lshlrev_b32_e32 v148, 16, v150
	v_and_b32_e32 v149, 0xffff0000, v150
	v_lshlrev_b32_e32 v150, 16, v151
	v_and_b32_e32 v151, 0xffff0000, v151
	v_lshlrev_b32_e32 v152, 16, v196
	v_and_b32_e32 v153, 0xffff0000, v196
	v_lshlrev_b32_e32 v154, 16, v197
	v_and_b32_e32 v155, 0xffff0000, v197
	v_pk_fma_f32 v[150:151], v[104:105], v[144:145], v[150:151]
	v_pk_fma_f32 v[148:149], v[102:103], v[142:143], v[148:149]
	v_pk_fma_f32 v[154:155], v[100:101], v[140:141], v[154:155]
	v_pk_fma_f32 v[152:153], v[98:99], v[138:139], v[152:153]
	v_cvt_pk_bf16_f32 v148, v148, v149
	v_cvt_pk_bf16_f32 v149, v150, v151
	v_cvt_pk_bf16_f32 v150, v152, v153
	v_cvt_pk_bf16_f32 v151, v154, v155
	v_permlane16_swap_b32_e32 v146, v198
	v_permlane16_swap_b32_e32 v147, v199
	v_permlane16_swap_b32_e32 v148, v150
	v_permlane16_swap_b32_e32 v149, v151
	flat_store_dwordx4 v[160:161], v[148:151]
	v_lshlrev_b32_e32 v152, 16, v199
	v_and_b32_e32 v153, 0xffff0000, v199
	v_lshlrev_b32_e32 v148, 16, v146
	v_and_b32_e32 v149, 0xffff0000, v146
	v_lshlrev_b32_e32 v146, 16, v147
	v_and_b32_e32 v147, 0xffff0000, v147
	v_pk_fma_f32 v[150:151], v[72:73], v[136:137], v[146:147]
	v_pk_fma_f32 v[146:147], v[70:71], v[134:135], v[148:149]
	v_lshlrev_b32_e32 v148, 16, v198
	v_and_b32_e32 v149, 0xffff0000, v198
	v_pk_fma_f32 v[152:153], v[68:69], v[132:133], v[152:153]
	v_pk_fma_f32 v[148:149], v[66:67], v[130:131], v[148:149]
	v_cvt_pk_bf16_f32 v146, v146, v147
	v_cvt_pk_bf16_f32 v147, v150, v151
	v_cvt_pk_bf16_f32 v148, v148, v149
	v_cvt_pk_bf16_f32 v149, v152, v153
	s_nop 0
	v_permlane16_swap_b32_e32 v146, v148
	v_permlane16_swap_b32_e32 v147, v149
	flat_store_dwordx4 v[160:161], v[146:149] offset:64
	s_mov_b32 s27, 0x40000
	v_add_co_u32_e32 v190, vcc, s27, v158
	s_mov_b32 s27, 0x48000
	s_nop 0
	v_addc_co_u32_e32 v191, vcc, 0, v159, vcc
	v_add_co_u32_e32 v192, vcc, s27, v158
	s_mov_b32 s27, 0x50000
	s_nop 0
	v_addc_co_u32_e32 v193, vcc, 0, v159, vcc
	v_add_co_u32_e32 v160, vcc, s27, v158
	s_mov_b64 s[56:57], 0x40000
	s_nop 0
	v_addc_co_u32_e32 v161, vcc, 0, v159, vcc
	s_mov_b32 s27, 0x58000
	v_lshl_add_u64 v[162:163], v[158:159], 0, s[56:57]
	v_add_co_u32_e32 v158, vcc, s27, v158
	v_mov_b32_e32 v170, v216
	v_mov_b32_e32 v171, v217
	v_mov_b32_e32 v172, v218
	v_mov_b32_e32 v173, v219
	v_mov_b32_e32 v174, v220
	v_mov_b32_e32 v175, v221
	v_mov_b32_e32 v176, v222
	v_mov_b32_e32 v177, v223
	v_addc_co_u32_e32 v159, vcc, 0, v159, vcc
	v_mov_b32_e32 v178, v224
	v_mov_b32_e32 v179, v225
	v_mov_b32_e32 v180, v226
	v_mov_b32_e32 v181, v227
	v_mov_b32_e32 v182, v228
	v_mov_b32_e32 v183, v229
	v_mov_b32_e32 v184, v230
	v_mov_b32_e32 v185, v231
	v_mov_b32_e32 v186, v232
	v_mov_b32_e32 v187, v233
	v_mov_b32_e32 v188, v234
	v_mov_b32_e32 v189, v235
	v_mov_b32_e32 v154, v240
	v_mov_b32_e32 v155, v241
	v_mov_b32_e32 v156, v242
	v_mov_b32_e32 v157, v243
	v_mov_b32_e32 v150, v244
	v_mov_b32_e32 v151, v245
	v_mov_b32_e32 v152, v246
	v_mov_b32_e32 v153, v247
	v_mov_b32_e32 v146, v202
	v_mov_b32_e32 v147, v203
	v_mov_b32_e32 v148, v204
	v_mov_b32_e32 v149, v205
	v_mov_b32_e32 v0, v172
	v_mov_b32_e32 v172, v173
	s_nop 0
	v_permlane16_swap_b32_e32 v170, v0
	v_permlane16_swap_b32_e32 v171, v172
	v_mov_b32_e32 v196, v156
	v_mov_b32_e32 v197, v157
	v_mov_b32_e32 v198, v152
	v_mov_b32_e32 v199, v153
	v_mov_b32_e32 v200, v148
	v_mov_b32_e32 v201, v149
	v_lshlrev_b32_e32 v148, 16, v170
	v_and_b32_e32 v149, 0xffff0000, v170
	v_lshlrev_b32_e32 v152, 16, v171
	v_and_b32_e32 v153, 0xffff0000, v171
	v_lshlrev_b32_e32 v156, 16, v0
	v_and_b32_e32 v157, 0xffff0000, v0
	v_lshlrev_b32_e32 v170, 16, v172
	v_and_b32_e32 v171, 0xffff0000, v172
	v_mov_b32_e32 v194, v176
	v_mov_b32_e32 v195, v177
	v_pk_fma_f32 v[152:153], v[64:65], v[144:145], v[152:153]
	v_pk_fma_f32 v[148:149], v[62:63], v[142:143], v[148:149]
	v_pk_fma_f32 v[176:177], v[60:61], v[140:141], v[170:171]
	v_pk_fma_f32 v[156:157], v[58:59], v[138:139], v[156:157]
	v_cvt_pk_bf16_f32 v170, v148, v149
	v_cvt_pk_bf16_f32 v171, v152, v153
	v_cvt_pk_bf16_f32 v172, v156, v157
	v_cvt_pk_bf16_f32 v173, v176, v177
	v_permlane16_swap_b32_e32 v174, v194
	v_permlane16_swap_b32_e32 v175, v195
	v_permlane16_swap_b32_e32 v170, v172
	v_permlane16_swap_b32_e32 v171, v173
	flat_store_dwordx4 v[190:191], v[170:173]
	v_lshlrev_b32_e32 v148, 16, v174
	v_and_b32_e32 v149, 0xffff0000, v174
	v_lshlrev_b32_e32 v152, 16, v175
	v_and_b32_e32 v153, 0xffff0000, v175
	v_lshlrev_b32_e32 v156, 16, v194
	v_and_b32_e32 v157, 0xffff0000, v194
	v_lshlrev_b32_e32 v170, 16, v195
	v_and_b32_e32 v171, 0xffff0000, v195
	v_pk_fma_f32 v[152:153], v[32:33], v[136:137], v[152:153]
	v_pk_fma_f32 v[148:149], v[30:31], v[134:135], v[148:149]
	v_pk_fma_f32 v[174:175], v[28:29], v[132:133], v[170:171]
	v_pk_fma_f32 v[156:157], v[26:27], v[130:131], v[156:157]
	v_cvt_pk_bf16_f32 v170, v148, v149
	v_cvt_pk_bf16_f32 v171, v152, v153
	v_cvt_pk_bf16_f32 v172, v156, v157
	v_cvt_pk_bf16_f32 v173, v174, v175
	v_permlane16_swap_b32_e32 v178, v180
	v_permlane16_swap_b32_e32 v179, v181
	v_permlane16_swap_b32_e32 v170, v172
	v_permlane16_swap_b32_e32 v171, v173
	flat_store_dwordx4 v[162:163], v[170:173] offset:64
	v_lshlrev_b32_e32 v148, 16, v178
	v_and_b32_e32 v149, 0xffff0000, v178
	v_lshlrev_b32_e32 v152, 16, v179
	v_and_b32_e32 v153, 0xffff0000, v179
	v_lshlrev_b32_e32 v156, 16, v180
	v_and_b32_e32 v157, 0xffff0000, v180
	v_lshlrev_b32_e32 v162, 16, v181
	v_and_b32_e32 v163, 0xffff0000, v181
	v_permlane16_swap_b32_e32 v182, v184
	v_permlane16_swap_b32_e32 v183, v185
	v_pk_fma_f32 v[152:153], v[56:57], v[144:145], v[152:153]
	v_pk_fma_f32 v[148:149], v[54:55], v[142:143], v[148:149]
	v_pk_fma_f32 v[162:163], v[52:53], v[140:141], v[162:163]
	v_pk_fma_f32 v[156:157], v[50:51], v[138:139], v[156:157]
	v_cvt_pk_bf16_f32 v170, v148, v149
	v_cvt_pk_bf16_f32 v171, v152, v153
	v_cvt_pk_bf16_f32 v172, v156, v157
	v_cvt_pk_bf16_f32 v173, v162, v163
	v_lshlrev_b32_e32 v148, 16, v182
	v_and_b32_e32 v149, 0xffff0000, v182
	v_lshlrev_b32_e32 v152, 16, v183
	v_and_b32_e32 v153, 0xffff0000, v183
	v_lshlrev_b32_e32 v156, 16, v184
	v_and_b32_e32 v157, 0xffff0000, v184
	v_lshlrev_b32_e32 v162, 16, v185
	v_and_b32_e32 v163, 0xffff0000, v185
	v_permlane16_swap_b32_e32 v186, v188
	v_permlane16_swap_b32_e32 v187, v189
	v_permlane16_swap_b32_e32 v170, v172
	v_permlane16_swap_b32_e32 v171, v173
	v_pk_fma_f32 v[152:153], v[24:25], v[136:137], v[152:153]
	v_pk_fma_f32 v[148:149], v[22:23], v[134:135], v[148:149]
	v_pk_fma_f32 v[162:163], v[20:21], v[132:133], v[162:163]
	v_pk_fma_f32 v[156:157], v[18:19], v[130:131], v[156:157]
	flat_store_dwordx4 v[192:193], v[170:173]
	v_permlane16_swap_b32_e32 v154, v196
	s_nop 0
	v_cvt_pk_bf16_f32 v170, v148, v149
	v_cvt_pk_bf16_f32 v171, v152, v153
	v_cvt_pk_bf16_f32 v172, v156, v157
	v_cvt_pk_bf16_f32 v173, v162, v163
	v_lshlrev_b32_e32 v148, 16, v186
	v_and_b32_e32 v149, 0xffff0000, v186
	v_lshlrev_b32_e32 v152, 16, v187
	v_and_b32_e32 v153, 0xffff0000, v187
	v_permlane16_swap_b32_e32 v155, v197
	v_permlane16_swap_b32_e32 v170, v172
	v_permlane16_swap_b32_e32 v171, v173
	v_pk_fma_f32 v[152:153], v[48:49], v[144:145], v[152:153]
	v_pk_fma_f32 v[148:149], v[46:47], v[142:143], v[148:149]
	flat_store_dwordx4 v[192:193], v[170:173] offset:64
	v_lshlrev_b32_e32 v162, 16, v189
	v_and_b32_e32 v163, 0xffff0000, v189
	v_cvt_pk_bf16_f32 v170, v148, v149
	v_cvt_pk_bf16_f32 v171, v152, v153
	v_lshlrev_b32_e32 v148, 16, v154
	v_and_b32_e32 v149, 0xffff0000, v154
	v_lshlrev_b32_e32 v152, 16, v155
	v_and_b32_e32 v153, 0xffff0000, v155
	v_permlane16_swap_b32_e32 v150, v198
	v_permlane16_swap_b32_e32 v151, v199
	v_pk_fma_f32 v[162:163], v[44:45], v[140:141], v[162:163]
	v_pk_fma_f32 v[154:155], v[16:17], v[136:137], v[152:153]
	v_pk_fma_f32 v[148:149], v[14:15], v[134:135], v[148:149]
	v_lshlrev_b32_e32 v152, 16, v196
	v_and_b32_e32 v153, 0xffff0000, v196
	v_cvt_pk_bf16_f32 v173, v162, v163
	v_pk_fma_f32 v[162:163], v[10:11], v[130:131], v[152:153]
	v_cvt_pk_bf16_f32 v152, v148, v149
	v_lshlrev_b32_e32 v148, 16, v150
	v_and_b32_e32 v149, 0xffff0000, v150
	v_lshlrev_b32_e32 v150, 16, v151
	v_and_b32_e32 v151, 0xffff0000, v151
	v_pk_fma_f32 v[144:145], v[40:41], v[144:145], v[150:151]
	v_pk_fma_f32 v[142:143], v[38:39], v[142:143], v[148:149]
	v_lshlrev_b32_e32 v148, 16, v198
	v_and_b32_e32 v149, 0xffff0000, v198
	v_lshlrev_b32_e32 v150, 16, v199
	v_and_b32_e32 v151, 0xffff0000, v199
	v_lshlrev_b32_e32 v156, 16, v188
	v_and_b32_e32 v157, 0xffff0000, v188
	v_pk_fma_f32 v[150:151], v[36:37], v[140:141], v[150:151]
	v_pk_fma_f32 v[140:141], v[34:35], v[138:139], v[148:149]
	v_pk_fma_f32 v[156:157], v[42:43], v[138:139], v[156:157]
	v_cvt_pk_bf16_f32 v138, v142, v143
	v_cvt_pk_bf16_f32 v139, v144, v145
	v_cvt_pk_bf16_f32 v140, v140, v141
	v_cvt_pk_bf16_f32 v141, v150, v151
	v_permlane16_swap_b32_e32 v146, v200
	v_permlane16_swap_b32_e32 v147, v201
	v_permlane16_swap_b32_e32 v138, v140
	v_permlane16_swap_b32_e32 v139, v141
	flat_store_dwordx4 v[158:159], v[138:141]
	v_cvt_pk_bf16_f32 v172, v156, v157
	v_lshlrev_b32_e32 v156, 16, v197
	v_lshlrev_b32_e32 v138, 16, v146
	v_and_b32_e32 v139, 0xffff0000, v146
	v_lshlrev_b32_e32 v140, 16, v147
	v_and_b32_e32 v141, 0xffff0000, v147
	v_and_b32_e32 v157, 0xffff0000, v197
	v_pk_fma_f32 v[136:137], v[8:9], v[136:137], v[140:141]
	v_pk_fma_f32 v[134:135], v[6:7], v[134:135], v[138:139]
	v_lshlrev_b32_e32 v138, 16, v200
	v_and_b32_e32 v139, 0xffff0000, v200
	v_lshlrev_b32_e32 v140, 16, v201
	v_and_b32_e32 v141, 0xffff0000, v201
	v_pk_fma_f32 v[156:157], v[12:13], v[132:133], v[156:157]
	v_pk_fma_f32 v[140:141], v[4:5], v[132:133], v[140:141]
	v_pk_fma_f32 v[132:133], v[2:3], v[130:131], v[138:139]
	v_cvt_pk_bf16_f32 v153, v154, v155
	v_cvt_pk_bf16_f32 v154, v162, v163
	v_cvt_pk_bf16_f32 v155, v156, v157
	v_cvt_pk_bf16_f32 v130, v134, v135
	v_cvt_pk_bf16_f32 v131, v136, v137
	v_cvt_pk_bf16_f32 v132, v132, v133
	v_cvt_pk_bf16_f32 v133, v140, v141
	v_permlane16_swap_b32_e32 v170, v172
	v_permlane16_swap_b32_e32 v171, v173
	v_permlane16_swap_b32_e32 v152, v154
	v_permlane16_swap_b32_e32 v153, v155
	v_permlane16_swap_b32_e32 v130, v132
	v_permlane16_swap_b32_e32 v131, v133
	flat_store_dwordx4 v[160:161], v[170:173]
	flat_store_dwordx4 v[160:161], v[152:155] offset:64
	flat_store_dwordx4 v[158:159], v[130:133] offset:64
	s_and_b64 vcc, exec, s[40:41]
	s_movk_i32 s92, 0x2000
	s_cbranch_vccnz .LBB0_128
	s_andn2_b64 vcc, exec, s[44:45]
	s_cbranch_vccnz .LBB0_116
	s_barrier
	s_branch .LBB0_116

.LBB0_372:
	s_add_u32 s26, s42, s25
	s_addc_u32 s27, s43, 0
	s_add_u32 s30, s26, 0x100
	s_addc_u32 s31, s27, 0
	s_and_b64 s[26:27], s[56:57], exec
	s_cselect_b32 s65, s53, s31
	s_cselect_b32 s64, s52, s30
	s_add_u32 s26, s44, s25
	s_addc_u32 s27, s45, 0
	s_add_u32 s30, s26, 0x100
	s_addc_u32 s31, s27, 0
	s_add_u32 s58, s64, 0x80
	s_addc_u32 s59, s65, 0
	s_and_b64 s[26:27], s[56:57], exec
	s_cselect_b32 s67, s55, s31
	s_cselect_b32 s66, s54, s30
	s_add_u32 s25, s10, s25
	s_addc_u32 s26, s24, 0
	s_add_u32 s70, s25, 0x80
	s_addc_u32 s71, s26, 0
	v_add_u32_e32 v0, 0x10000, v154
	s_add_u32 s68, s66, s20
	ds_read_b128 v[38:41], v0
	ds_read_b128 v[42:45], v0 offset:1024
	ds_read_b128 v[50:53], v0 offset:2048
	ds_read_b128 v[54:57], v0 offset:3072
	v_add_u32_e32 v0, 0x14000, v154
	s_addc_u32 s69, s67, s21
	ds_read_b128 v[146:149], v0
	ds_read_b128 v[156:159], v0 offset:1024
	ds_read_b128 v[160:163], v0 offset:2048
	ds_read_b128 v[164:167], v0 offset:3072
	s_add_u32 s62, s64, s4
	s_addc_u32 s63, s65, s5
	s_add_u32 s60, s66, 0x80
	s_addc_u32 s61, s67, 0
	s_add_u32 s56, s68, 0x80
	s_addc_u32 s57, s69, 0
	ds_read_b128 v[168:171], v155
	ds_read_b128 v[172:175], v155 offset:1024
	ds_read_b128 v[176:179], v155 offset:2048
	ds_read_b128 v[202:205], v155 offset:3072
	ds_read_b128 v[206:209], v155 offset:4096
	ds_read_b128 v[216:219], v155 offset:5120
	ds_read_b128 v[220:223], v155 offset:6144
	ds_read_b128 v[224:227], v155 offset:7168
	s_mov_b32 m0, s46
	s_nop 0
	global_load_lds_dwordx4 v150, s[70:71]
	s_mov_b32 m0, s47
	s_nop 0
	global_load_lds_dwordx4 v152, s[70:71]
	s_waitcnt vmcnt(8) lgkmcnt(0)
	s_setprio 1
	s_barrier
	v_mfma_f32_16x16x32_bf16 v[142:145], v[38:41], v[168:171], v[142:145]
	v_mfma_f32_16x16x32_bf16 v[138:141], v[50:53], v[168:171], v[138:141]
	v_mfma_f32_16x16x32_bf16 v[126:129], v[38:41], v[176:179], v[126:129]
	v_mfma_f32_16x16x32_bf16 v[122:125], v[50:53], v[176:179], v[122:125]
	v_mfma_f32_16x16x32_bf16 v[110:113], v[38:41], v[206:209], v[110:113]
	v_mfma_f32_16x16x32_bf16 v[106:109], v[50:53], v[206:209], v[106:109]
	v_mfma_f32_16x16x32_bf16 v[94:97], v[38:41], v[220:223], v[94:97]
	v_mfma_f32_16x16x32_bf16 v[90:93], v[50:53], v[220:223], v[90:93]
	v_mfma_f32_16x16x32_bf16 v[142:145], v[42:45], v[172:175], v[142:145]
	v_mfma_f32_16x16x32_bf16 v[138:141], v[54:57], v[172:175], v[138:141]
	v_mfma_f32_16x16x32_bf16 v[126:129], v[42:45], v[202:205], v[126:129]
	v_mfma_f32_16x16x32_bf16 v[122:125], v[54:57], v[202:205], v[122:125]
	v_mfma_f32_16x16x32_bf16 v[110:113], v[42:45], v[216:219], v[110:113]
	v_mfma_f32_16x16x32_bf16 v[106:109], v[54:57], v[216:219], v[106:109]
	v_mfma_f32_16x16x32_bf16 v[94:97], v[42:45], v[224:227], v[94:97]
	v_mfma_f32_16x16x32_bf16 v[90:93], v[54:57], v[224:227], v[90:93]
	v_mfma_f32_16x16x32_bf16 v[134:137], v[146:149], v[168:171], v[134:137]
	v_mfma_f32_16x16x32_bf16 v[130:133], v[160:163], v[168:171], v[130:133]
	v_mfma_f32_16x16x32_bf16 v[118:121], v[146:149], v[176:179], v[118:121]
	v_mfma_f32_16x16x32_bf16 v[114:117], v[160:163], v[176:179], v[114:117]
	v_mfma_f32_16x16x32_bf16 v[102:105], v[146:149], v[206:209], v[102:105]
	v_mfma_f32_16x16x32_bf16 v[98:101], v[160:163], v[206:209], v[98:101]
	v_mfma_f32_16x16x32_bf16 v[86:89], v[146:149], v[220:223], v[86:89]
	v_mfma_f32_16x16x32_bf16 v[82:85], v[160:163], v[220:223], v[82:85]
	v_mfma_f32_16x16x32_bf16 v[134:137], v[156:159], v[172:175], v[134:137]
	v_mfma_f32_16x16x32_bf16 v[130:133], v[164:167], v[172:175], v[130:133]
	v_mfma_f32_16x16x32_bf16 v[118:121], v[156:159], v[202:205], v[118:121]
	v_mfma_f32_16x16x32_bf16 v[114:117], v[164:167], v[202:205], v[114:117]
	v_mfma_f32_16x16x32_bf16 v[102:105], v[156:159], v[216:219], v[102:105]
	v_mfma_f32_16x16x32_bf16 v[98:101], v[164:167], v[216:219], v[98:101]
	v_mfma_f32_16x16x32_bf16 v[86:89], v[156:159], v[224:227], v[86:89]
	v_mfma_f32_16x16x32_bf16 v[82:85], v[164:167], v[224:227], v[82:85]
	s_setprio 0
	s_barrier
	ds_read_b128 v[168:171], v155 offset:16384
	ds_read_b128 v[172:175], v155 offset:17408
	ds_read_b128 v[176:179], v155 offset:18432
	ds_read_b128 v[202:205], v155 offset:19456
	ds_read_b128 v[206:209], v155 offset:20480
	ds_read_b128 v[216:219], v155 offset:21504
	ds_read_b128 v[220:223], v155 offset:22528
	ds_read_b128 v[224:227], v155 offset:23552
	s_mov_b32 m0, s78
	s_nop 0
	global_load_lds_dwordx4 v151, s[66:67]
	s_mov_b32 m0, s79
	s_nop 0
	global_load_lds_dwordx4 v153, s[66:67]
	s_nop 0
	s_mov_b32 m0, s80
	s_nop 0
	global_load_lds_dwordx4 v151, s[68:69]
	s_mov_b32 m0, s81
	s_nop 0
	global_load_lds_dwordx4 v153, s[68:69]
	s_nop 0
	s_mov_b32 m0, s75
	s_nop 0
	global_load_lds_dwordx4 v150, s[64:65]
	s_mov_b32 m0, s82
	s_nop 0
	global_load_lds_dwordx4 v152, s[64:65]
	s_waitcnt vmcnt(8) lgkmcnt(0)
	s_setprio 1
	s_barrier
	v_mfma_f32_16x16x32_bf16 v[78:81], v[38:41], v[168:171], v[78:81]
	v_mfma_f32_16x16x32_bf16 v[74:77], v[50:53], v[168:171], v[74:77]
	v_mfma_f32_16x16x32_bf16 v[62:65], v[38:41], v[176:179], v[62:65]
	v_mfma_f32_16x16x32_bf16 v[58:61], v[50:53], v[176:179], v[58:61]
	v_mfma_f32_16x16x32_bf16 v[30:33], v[38:41], v[206:209], v[30:33]
	v_mfma_f32_16x16x32_bf16 v[26:29], v[50:53], v[206:209], v[26:29]
	v_mfma_f32_16x16x32_bf16 v[14:17], v[38:41], v[220:223], v[14:17]
	v_mfma_f32_16x16x32_bf16 v[10:13], v[50:53], v[220:223], v[10:13]
	v_mfma_f32_16x16x32_bf16 v[78:81], v[42:45], v[172:175], v[78:81]
	v_mfma_f32_16x16x32_bf16 v[74:77], v[54:57], v[172:175], v[74:77]
	v_mfma_f32_16x16x32_bf16 v[62:65], v[42:45], v[202:205], v[62:65]
	v_mfma_f32_16x16x32_bf16 v[58:61], v[54:57], v[202:205], v[58:61]
	v_mfma_f32_16x16x32_bf16 v[30:33], v[42:45], v[216:219], v[30:33]
	v_mfma_f32_16x16x32_bf16 v[26:29], v[54:57], v[216:219], v[26:29]
	v_mfma_f32_16x16x32_bf16 v[14:17], v[42:45], v[224:227], v[14:17]
	v_mfma_f32_16x16x32_bf16 v[10:13], v[54:57], v[224:227], v[10:13]
	v_mfma_f32_16x16x32_bf16 v[46:49], v[146:149], v[176:179], v[46:49]
	v_mfma_f32_16x16x32_bf16 v[34:37], v[160:163], v[176:179], v[34:37]
	v_mfma_f32_16x16x32_bf16 v[22:25], v[146:149], v[206:209], v[22:25]
	v_mfma_f32_16x16x32_bf16 v[18:21], v[160:163], v[206:209], v[18:21]
	v_mfma_f32_16x16x32_bf16 v[6:9], v[146:149], v[220:223], v[6:9]
	v_mfma_f32_16x16x32_bf16 v[2:5], v[160:163], v[220:223], v[2:5]
	v_mfma_f32_16x16x32_bf16 v[38:41], v[146:149], v[168:171], v[70:73]
	v_mfma_f32_16x16x32_bf16 v[42:45], v[160:163], v[168:171], v[66:69]
	v_mfma_f32_16x16x32_bf16 v[46:49], v[156:159], v[202:205], v[46:49]
	v_mfma_f32_16x16x32_bf16 v[34:37], v[164:167], v[202:205], v[34:37]
	v_mfma_f32_16x16x32_bf16 v[22:25], v[156:159], v[216:219], v[22:25]
	v_mfma_f32_16x16x32_bf16 v[18:21], v[164:167], v[216:219], v[18:21]
	v_mfma_f32_16x16x32_bf16 v[6:9], v[156:159], v[224:227], v[6:9]
	v_mfma_f32_16x16x32_bf16 v[2:5], v[164:167], v[224:227], v[2:5]
	v_mfma_f32_16x16x32_bf16 v[38:41], v[156:159], v[172:175], v[38:41]
	v_mfma_f32_16x16x32_bf16 v[42:45], v[164:167], v[172:175], v[42:45]
	s_setprio 0
	s_barrier
	v_add_u32_e32 v0, 0x18000, v154
	ds_read_b128 v[50:53], v0
	ds_read_b128 v[54:57], v0 offset:1024
	ds_read_b128 v[66:69], v0 offset:2048
	ds_read_b128 v[70:73], v0 offset:3072
	v_add_u32_e32 v0, 0x1c000, v154
	ds_read_b128 v[146:149], v0
	ds_read_b128 v[156:159], v0 offset:1024
	ds_read_b128 v[160:163], v0 offset:2048
	ds_read_b128 v[164:167], v0 offset:3072
	ds_read_b128 v[168:171], v155 offset:32768
	ds_read_b128 v[172:175], v155 offset:33792
	ds_read_b128 v[176:179], v155 offset:34816
	ds_read_b128 v[202:205], v155 offset:35840
	ds_read_b128 v[206:209], v155 offset:36864
	ds_read_b128 v[216:219], v155 offset:37888
	ds_read_b128 v[220:223], v155 offset:38912
	ds_read_b128 v[224:227], v155 offset:39936
	s_mov_b32 m0, s83
	s_nop 0
	global_load_lds_dwordx4 v150, s[62:63]
	s_mov_b32 m0, s84
	s_nop 0
	global_load_lds_dwordx4 v152, s[62:63]
	s_waitcnt vmcnt(8) lgkmcnt(0)
	s_setprio 1
	s_barrier
	v_mfma_f32_16x16x32_bf16 v[142:145], v[50:53], v[168:171], v[142:145]
	v_mfma_f32_16x16x32_bf16 v[138:141], v[66:69], v[168:171], v[138:141]
	v_mfma_f32_16x16x32_bf16 v[126:129], v[50:53], v[176:179], v[126:129]
	v_mfma_f32_16x16x32_bf16 v[122:125], v[66:69], v[176:179], v[122:125]
	v_mfma_f32_16x16x32_bf16 v[110:113], v[50:53], v[206:209], v[110:113]
	v_mfma_f32_16x16x32_bf16 v[106:109], v[66:69], v[206:209], v[106:109]
	v_mfma_f32_16x16x32_bf16 v[94:97], v[50:53], v[220:223], v[94:97]
	v_mfma_f32_16x16x32_bf16 v[90:93], v[66:69], v[220:223], v[90:93]
	v_mfma_f32_16x16x32_bf16 v[142:145], v[54:57], v[172:175], v[142:145]
	v_mfma_f32_16x16x32_bf16 v[138:141], v[70:73], v[172:175], v[138:141]
	v_mfma_f32_16x16x32_bf16 v[126:129], v[54:57], v[202:205], v[126:129]
	v_mfma_f32_16x16x32_bf16 v[122:125], v[70:73], v[202:205], v[122:125]
	v_mfma_f32_16x16x32_bf16 v[110:113], v[54:57], v[216:219], v[110:113]
	v_mfma_f32_16x16x32_bf16 v[106:109], v[70:73], v[216:219], v[106:109]
	v_mfma_f32_16x16x32_bf16 v[94:97], v[54:57], v[224:227], v[94:97]
	v_mfma_f32_16x16x32_bf16 v[90:93], v[70:73], v[224:227], v[90:93]
	v_mfma_f32_16x16x32_bf16 v[134:137], v[146:149], v[168:171], v[134:137]
	v_mfma_f32_16x16x32_bf16 v[130:133], v[160:163], v[168:171], v[130:133]
	v_mfma_f32_16x16x32_bf16 v[118:121], v[146:149], v[176:179], v[118:121]
	v_mfma_f32_16x16x32_bf16 v[114:117], v[160:163], v[176:179], v[114:117]
	v_mfma_f32_16x16x32_bf16 v[102:105], v[146:149], v[206:209], v[102:105]
	v_mfma_f32_16x16x32_bf16 v[98:101], v[160:163], v[206:209], v[98:101]
	v_mfma_f32_16x16x32_bf16 v[86:89], v[146:149], v[220:223], v[86:89]
	v_mfma_f32_16x16x32_bf16 v[82:85], v[160:163], v[220:223], v[82:85]
	v_mfma_f32_16x16x32_bf16 v[134:137], v[156:159], v[172:175], v[134:137]
	v_mfma_f32_16x16x32_bf16 v[130:133], v[164:167], v[172:175], v[130:133]
	v_mfma_f32_16x16x32_bf16 v[118:121], v[156:159], v[202:205], v[118:121]
	v_mfma_f32_16x16x32_bf16 v[114:117], v[164:167], v[202:205], v[114:117]
	v_mfma_f32_16x16x32_bf16 v[102:105], v[156:159], v[216:219], v[102:105]
	v_mfma_f32_16x16x32_bf16 v[98:101], v[164:167], v[216:219], v[98:101]
	v_mfma_f32_16x16x32_bf16 v[86:89], v[156:159], v[224:227], v[86:89]
	v_mfma_f32_16x16x32_bf16 v[82:85], v[164:167], v[224:227], v[82:85]
	s_setprio 0
	s_barrier
	ds_read_b128 v[168:171], v155 offset:49152
	ds_read_b128 v[172:175], v155 offset:50176
	ds_read_b128 v[176:179], v155 offset:51200
	ds_read_b128 v[202:205], v155 offset:52224
	ds_read_b128 v[206:209], v155 offset:53248
	ds_read_b128 v[216:219], v155 offset:54272
	ds_read_b128 v[220:223], v155 offset:55296
	ds_read_b128 v[224:227], v155 offset:56320
	s_mov_b32 m0, s87
	s_nop 0
	global_load_lds_dwordx4 v151, s[60:61]
	s_mov_b32 m0, s88
	s_nop 0
	global_load_lds_dwordx4 v153, s[60:61]
	s_nop 0
	s_mov_b32 m0, s91
	s_nop 0
	global_load_lds_dwordx4 v151, s[56:57]
	s_mov_b32 m0, s97
	s_nop 0
	global_load_lds_dwordx4 v153, s[56:57]
	s_nop 0
	s_mov_b32 m0, s89
	s_nop 0
	global_load_lds_dwordx4 v150, s[58:59]
	s_mov_b32 m0, s90
	s_nop 0
	global_load_lds_dwordx4 v152, s[58:59]
	s_waitcnt vmcnt(8) lgkmcnt(0)
	s_setprio 1
	s_barrier
	v_mfma_f32_16x16x32_bf16 v[78:81], v[50:53], v[168:171], v[78:81]
	v_mfma_f32_16x16x32_bf16 v[74:77], v[66:69], v[168:171], v[74:77]
	v_mfma_f32_16x16x32_bf16 v[62:65], v[50:53], v[176:179], v[62:65]
	v_mfma_f32_16x16x32_bf16 v[58:61], v[66:69], v[176:179], v[58:61]
	v_mfma_f32_16x16x32_bf16 v[30:33], v[50:53], v[206:209], v[30:33]
	v_mfma_f32_16x16x32_bf16 v[26:29], v[66:69], v[206:209], v[26:29]
	v_mfma_f32_16x16x32_bf16 v[14:17], v[50:53], v[220:223], v[14:17]
	v_mfma_f32_16x16x32_bf16 v[10:13], v[66:69], v[220:223], v[10:13]
	v_mfma_f32_16x16x32_bf16 v[78:81], v[54:57], v[172:175], v[78:81]
	v_mfma_f32_16x16x32_bf16 v[74:77], v[70:73], v[172:175], v[74:77]
	v_mfma_f32_16x16x32_bf16 v[62:65], v[54:57], v[202:205], v[62:65]
	v_mfma_f32_16x16x32_bf16 v[58:61], v[70:73], v[202:205], v[58:61]
	v_mfma_f32_16x16x32_bf16 v[30:33], v[54:57], v[216:219], v[30:33]
	v_mfma_f32_16x16x32_bf16 v[26:29], v[70:73], v[216:219], v[26:29]
	v_mfma_f32_16x16x32_bf16 v[14:17], v[54:57], v[224:227], v[14:17]
	v_mfma_f32_16x16x32_bf16 v[10:13], v[70:73], v[224:227], v[10:13]
	v_mfma_f32_16x16x32_bf16 v[38:41], v[146:149], v[168:171], v[38:41]
	v_mfma_f32_16x16x32_bf16 v[70:73], v[156:159], v[172:175], v[38:41]
	v_mfma_f32_16x16x32_bf16 v[38:41], v[160:163], v[168:171], v[42:45]
	v_mfma_f32_16x16x32_bf16 v[66:69], v[164:167], v[172:175], v[38:41]
	v_mfma_f32_16x16x32_bf16 v[38:41], v[146:149], v[176:179], v[46:49]
	v_mfma_f32_16x16x32_bf16 v[34:37], v[160:163], v[176:179], v[34:37]
	v_mfma_f32_16x16x32_bf16 v[22:25], v[146:149], v[206:209], v[22:25]
	v_mfma_f32_16x16x32_bf16 v[18:21], v[160:163], v[206:209], v[18:21]
	v_mfma_f32_16x16x32_bf16 v[6:9], v[146:149], v[220:223], v[6:9]
	v_mfma_f32_16x16x32_bf16 v[2:5], v[160:163], v[220:223], v[2:5]
	v_mfma_f32_16x16x32_bf16 v[46:49], v[156:159], v[202:205], v[38:41]
	v_mfma_f32_16x16x32_bf16 v[34:37], v[164:167], v[202:205], v[34:37]
	v_mfma_f32_16x16x32_bf16 v[22:25], v[156:159], v[216:219], v[22:25]
	v_mfma_f32_16x16x32_bf16 v[18:21], v[164:167], v[216:219], v[18:21]
	v_mfma_f32_16x16x32_bf16 v[6:9], v[156:159], v[224:227], v[6:9]
	v_mfma_f32_16x16x32_bf16 v[2:5], v[164:167], v[224:227], v[2:5]
	s_setprio 0
	s_barrier
	s_movk_i32 s25, 0x100
	s_andn2_b64 vcc, exec, s[40:41]
	s_mov_b64 s[56:57], -1
	s_mov_b64 s[40:41], 0
	s_cbranch_vccz .LBB0_372
	s_and_b64 vcc, exec, s[50:51]
	s_cbranch_vccz .LBB0_375
	s_barrier

.LBB0_439:
	v_add_u32_e32 v0, 0x10000, v152
	ds_read_b128 v[2:5], v0
	ds_read_b128 v[6:9], v0 offset:1024
	ds_read_b128 v[10:13], v0 offset:2048
	ds_read_b128 v[14:17], v0 offset:3072
	v_add_u32_e32 v0, 0x14000, v152
	ds_read_b128 v[18:21], v0
	ds_read_b128 v[22:25], v0 offset:1024
	ds_read_b128 v[26:29], v0 offset:2048
	ds_read_b128 v[30:33], v0 offset:3072
	s_add_u32 s58, s58, s4
	s_addc_u32 s59, s59, s5
	s_add_u32 s40, s56, 0x80
	s_addc_u32 s41, s57, 0
	ds_read_b128 v[34:37], v153
	ds_read_b128 v[38:41], v153 offset:1024
	ds_read_b128 v[42:45], v153 offset:2048
	ds_read_b128 v[46:49], v153 offset:3072
	ds_read_b128 v[50:53], v153 offset:4096
	ds_read_b128 v[54:57], v153 offset:5120
	ds_read_b128 v[58:61], v153 offset:6144
	s_waitcnt vmcnt(0)
	ds_read_b128 v[62:65], v153 offset:7168
	s_add_u32 s58, s58, 0x80
	s_addc_u32 s59, s59, 0
	s_mov_b32 m0, s67
	s_nop 0
	global_load_lds_dwordx4 v148, s[58:59]
	s_mov_b32 m0, s68
	s_nop 0
	global_load_lds_dwordx4 v150, s[58:59]
	s_waitcnt vmcnt(8) lgkmcnt(0)
	s_barrier
	s_setprio 1
	s_waitcnt lgkmcnt(0)
	v_mfma_f32_16x16x32_bf16 v[66:69], v[2:5], v[34:37], 0
	v_mfma_f32_16x16x32_bf16 v[70:73], v[10:13], v[34:37], 0
	v_mfma_f32_16x16x32_bf16 v[74:77], v[2:5], v[42:45], 0
	v_mfma_f32_16x16x32_bf16 v[78:81], v[10:13], v[42:45], 0
	s_waitcnt vmcnt(0)
	v_mfma_f32_16x16x32_bf16 v[82:85], v[2:5], v[50:53], 0
	v_mfma_f32_16x16x32_bf16 v[86:89], v[10:13], v[50:53], 0
	v_mfma_f32_16x16x32_bf16 v[90:93], v[2:5], v[58:61], 0
	v_mfma_f32_16x16x32_bf16 v[94:97], v[10:13], v[58:61], 0
	v_mfma_f32_16x16x32_bf16 v[66:69], v[6:9], v[38:41], v[66:69]
	v_mfma_f32_16x16x32_bf16 v[70:73], v[14:17], v[38:41], v[70:73]
	v_mfma_f32_16x16x32_bf16 v[74:77], v[6:9], v[46:49], v[74:77]
	v_mfma_f32_16x16x32_bf16 v[78:81], v[14:17], v[46:49], v[78:81]
	v_mfma_f32_16x16x32_bf16 v[82:85], v[6:9], v[54:57], v[82:85]
	v_mfma_f32_16x16x32_bf16 v[86:89], v[14:17], v[54:57], v[86:89]
	v_mfma_f32_16x16x32_bf16 v[90:93], v[6:9], v[62:65], v[90:93]
	v_mfma_f32_16x16x32_bf16 v[98:101], v[14:17], v[62:65], v[94:97]
	v_mfma_f32_16x16x32_bf16 v[94:97], v[18:21], v[34:37], 0
	v_mfma_f32_16x16x32_bf16 v[34:37], v[26:29], v[34:37], 0
	v_mfma_f32_16x16x32_bf16 v[102:105], v[22:25], v[38:41], v[94:97]
	v_mfma_f32_16x16x32_bf16 v[34:37], v[30:33], v[38:41], v[34:37]
	v_mfma_f32_16x16x32_bf16 v[38:41], v[18:21], v[42:45], 0
	v_mfma_f32_16x16x32_bf16 v[42:45], v[26:29], v[42:45], 0
	v_mfma_f32_16x16x32_bf16 v[38:41], v[22:25], v[46:49], v[38:41]
	v_mfma_f32_16x16x32_bf16 v[42:45], v[30:33], v[46:49], v[42:45]
	v_mfma_f32_16x16x32_bf16 v[46:49], v[18:21], v[50:53], 0
	v_mfma_f32_16x16x32_bf16 v[50:53], v[26:29], v[50:53], 0
	v_mfma_f32_16x16x32_bf16 v[46:49], v[22:25], v[54:57], v[46:49]
	v_mfma_f32_16x16x32_bf16 v[50:53], v[30:33], v[54:57], v[50:53]
	v_mfma_f32_16x16x32_bf16 v[54:57], v[18:21], v[58:61], 0
	v_mfma_f32_16x16x32_bf16 v[58:61], v[26:29], v[58:61], 0
	v_mfma_f32_16x16x32_bf16 v[54:57], v[22:25], v[62:65], v[54:57]
	v_mfma_f32_16x16x32_bf16 v[58:61], v[30:33], v[62:65], v[58:61]
	s_setprio 0
	s_barrier
	ds_read_b128 v[62:65], v153 offset:16384
	ds_read_b128 v[94:97], v153 offset:17408
	ds_read_b128 v[106:109], v153 offset:18432
	ds_read_b128 v[110:113], v153 offset:19456
	ds_read_b128 v[114:117], v153 offset:20480
	ds_read_b128 v[118:121], v153 offset:21504
	ds_read_b128 v[122:125], v153 offset:22528
	ds_read_b128 v[126:129], v153 offset:23552
	s_mov_b32 m0, s25
	s_nop 0
	global_load_lds_dwordx4 v149, s[42:43]
	s_mov_b32 m0, s26
	s_nop 0
	global_load_lds_dwordx4 v151, s[42:43]
	s_add_u32 s58, s42, s20
	s_addc_u32 s59, s43, s21
	s_mov_b32 m0, s27
	s_nop 0
	global_load_lds_dwordx4 v149, s[58:59]
	s_mov_b32 m0, s28
	s_nop 0
	global_load_lds_dwordx4 v151, s[58:59]
	s_nop 0
	s_mov_b32 m0, s24
	s_nop 0
	global_load_lds_dwordx4 v148, s[56:57]
	s_mov_b32 m0, s29
	s_nop 0
	global_load_lds_dwordx4 v150, s[56:57]
	s_waitcnt vmcnt(8) lgkmcnt(0)
	s_setprio 1
	s_barrier
	v_mfma_f32_16x16x32_bf16 v[130:133], v[2:5], v[62:65], 0
	v_mfma_f32_16x16x32_bf16 v[154:157], v[6:9], v[94:97], v[130:133]
	v_mfma_f32_16x16x32_bf16 v[130:133], v[10:13], v[62:65], 0
	v_mfma_f32_16x16x32_bf16 v[158:161], v[14:17], v[94:97], v[130:133]
	v_mfma_f32_16x16x32_bf16 v[130:133], v[2:5], v[106:109], 0
	v_mfma_f32_16x16x32_bf16 v[162:165], v[6:9], v[110:113], v[130:133]
	v_mfma_f32_16x16x32_bf16 v[130:133], v[10:13], v[106:109], 0
	v_mfma_f32_16x16x32_bf16 v[166:169], v[14:17], v[110:113], v[130:133]
	v_mfma_f32_16x16x32_bf16 v[130:133], v[2:5], v[114:117], 0
	v_mfma_f32_16x16x32_bf16 v[2:5], v[2:5], v[122:125], 0
	v_mfma_f32_16x16x32_bf16 v[170:173], v[6:9], v[118:121], v[130:133]
	v_mfma_f32_16x16x32_bf16 v[2:5], v[6:9], v[126:129], v[2:5]
	v_mfma_f32_16x16x32_bf16 v[6:9], v[10:13], v[122:125], 0
	v_mfma_f32_16x16x32_bf16 v[130:133], v[10:13], v[114:117], 0
	v_mfma_f32_16x16x32_bf16 v[6:9], v[14:17], v[126:129], v[6:9]
	v_mfma_f32_16x16x32_bf16 v[174:177], v[14:17], v[118:121], v[130:133]
	v_mfma_f32_16x16x32_bf16 v[10:13], v[18:21], v[62:65], 0
	v_mfma_f32_16x16x32_bf16 v[202:205], v[22:25], v[94:97], v[10:13]
	v_mfma_f32_16x16x32_bf16 v[10:13], v[26:29], v[62:65], 0
	v_mfma_f32_16x16x32_bf16 v[206:209], v[30:33], v[94:97], v[10:13]
	v_mfma_f32_16x16x32_bf16 v[10:13], v[18:21], v[106:109], 0
	v_mfma_f32_16x16x32_bf16 v[216:219], v[22:25], v[110:113], v[10:13]
	v_mfma_f32_16x16x32_bf16 v[10:13], v[26:29], v[106:109], 0
	v_mfma_f32_16x16x32_bf16 v[220:223], v[30:33], v[110:113], v[10:13]
	v_mfma_f32_16x16x32_bf16 v[10:13], v[18:21], v[114:117], 0
	v_mfma_f32_16x16x32_bf16 v[224:227], v[22:25], v[118:121], v[10:13]
	v_mfma_f32_16x16x32_bf16 v[10:13], v[26:29], v[114:117], 0
	v_mfma_f32_16x16x32_bf16 v[228:231], v[30:33], v[118:121], v[10:13]
	v_mfma_f32_16x16x32_bf16 v[10:13], v[18:21], v[122:125], 0
	v_mfma_f32_16x16x32_bf16 v[18:21], v[22:25], v[126:129], v[10:13]
	v_mfma_f32_16x16x32_bf16 v[10:13], v[26:29], v[122:125], 0
	v_mfma_f32_16x16x32_bf16 v[22:25], v[30:33], v[126:129], v[10:13]
	s_setprio 0
	s_barrier
	v_add_u32_e32 v0, 0x18000, v152
	s_nop 3
	ds_read_b128 v[10:13], v0
	ds_read_b128 v[14:17], v0 offset:1024
	ds_read_b128 v[26:29], v0 offset:2048
	ds_read_b128 v[30:33], v0 offset:3072
	v_add_u32_e32 v0, 0x1c000, v152
	ds_read_b128 v[232:235], v0
	ds_read_b128 v[236:239], v0 offset:1024
	ds_read_b128 v[240:243], v0 offset:2048
	ds_read_b128 v[244:247], v0 offset:3072
	ds_read_b128 v[62:65], v153 offset:32768
	ds_read_b128 v[114:117], v153 offset:33792
	ds_read_b128 v[198:201], v153 offset:34816
	ds_read_b128 v[182:185], v153 offset:35840
	ds_read_b128 v[190:193], v153 offset:36864
	ds_read_b128 v[194:197], v153 offset:37888
	ds_read_b128 v[186:189], v153 offset:38912
	ds_read_b128 v[178:181], v153 offset:39936
	s_add_u32 s78, s56, s4
	s_addc_u32 s79, s57, s5
	s_mov_b32 m0, s30
	s_nop 0
	global_load_lds_dwordx4 v148, s[78:79]
	s_mov_b32 m0, s31
	s_nop 0
	global_load_lds_dwordx4 v150, s[78:79]
	s_waitcnt vmcnt(8) lgkmcnt(0)
	s_setprio 1
	s_barrier
	v_mfma_f32_16x16x32_bf16 v[66:69], v[10:13], v[62:65], v[66:69]
	v_mfma_f32_16x16x32_bf16 v[142:145], v[14:17], v[114:117], v[66:69]
	v_mfma_f32_16x16x32_bf16 v[66:69], v[26:29], v[62:65], v[70:73]
	v_mfma_f32_16x16x32_bf16 v[138:141], v[30:33], v[114:117], v[66:69]
	v_mfma_f32_16x16x32_bf16 v[66:69], v[10:13], v[198:201], v[74:77]
	v_mfma_f32_16x16x32_bf16 v[126:129], v[14:17], v[182:185], v[66:69]
	v_mfma_f32_16x16x32_bf16 v[66:69], v[26:29], v[198:201], v[78:81]
	v_mfma_f32_16x16x32_bf16 v[122:125], v[30:33], v[182:185], v[66:69]
	v_mfma_f32_16x16x32_bf16 v[66:69], v[10:13], v[190:193], v[82:85]
	v_mfma_f32_16x16x32_bf16 v[110:113], v[14:17], v[194:197], v[66:69]
	v_mfma_f32_16x16x32_bf16 v[66:69], v[26:29], v[190:193], v[86:89]
	v_mfma_f32_16x16x32_bf16 v[106:109], v[30:33], v[194:197], v[66:69]
	v_mfma_f32_16x16x32_bf16 v[66:69], v[10:13], v[186:189], v[90:93]
	v_mfma_f32_16x16x32_bf16 v[94:97], v[14:17], v[178:181], v[66:69]
	v_mfma_f32_16x16x32_bf16 v[66:69], v[26:29], v[186:189], v[98:101]
	v_mfma_f32_16x16x32_bf16 v[90:93], v[30:33], v[178:181], v[66:69]
	v_mfma_f32_16x16x32_bf16 v[34:37], v[240:243], v[62:65], v[34:37]
	v_mfma_f32_16x16x32_bf16 v[130:133], v[244:247], v[114:117], v[34:37]
	v_mfma_f32_16x16x32_bf16 v[34:37], v[232:235], v[198:201], v[38:41]
	v_mfma_f32_16x16x32_bf16 v[66:69], v[232:235], v[62:65], v[102:105]
	v_mfma_f32_16x16x32_bf16 v[118:121], v[236:239], v[182:185], v[34:37]
	v_mfma_f32_16x16x32_bf16 v[34:37], v[240:243], v[198:201], v[42:45]
	v_mfma_f32_16x16x32_bf16 v[134:137], v[236:239], v[114:117], v[66:69]
	v_mfma_f32_16x16x32_bf16 v[114:117], v[244:247], v[182:185], v[34:37]
	v_mfma_f32_16x16x32_bf16 v[34:37], v[232:235], v[190:193], v[46:49]
	v_mfma_f32_16x16x32_bf16 v[102:105], v[236:239], v[194:197], v[34:37]
	v_mfma_f32_16x16x32_bf16 v[34:37], v[240:243], v[190:193], v[50:53]
	v_mfma_f32_16x16x32_bf16 v[98:101], v[244:247], v[194:197], v[34:37]
	v_mfma_f32_16x16x32_bf16 v[34:37], v[232:235], v[186:189], v[54:57]
	v_mfma_f32_16x16x32_bf16 v[86:89], v[236:239], v[178:181], v[34:37]
	v_mfma_f32_16x16x32_bf16 v[34:37], v[240:243], v[186:189], v[58:61]
	v_mfma_f32_16x16x32_bf16 v[82:85], v[244:247], v[178:181], v[34:37]
	s_setprio 0
	s_barrier
	s_nop 4
	ds_read_b128 v[34:37], v153 offset:49152
	ds_read_b128 v[38:41], v153 offset:50176
	ds_read_b128 v[50:53], v153 offset:51200
	ds_read_b128 v[178:181], v153 offset:52224
	ds_read_b128 v[182:185], v153 offset:53248
	ds_read_b128 v[186:189], v153 offset:54272
	ds_read_b128 v[190:193], v153 offset:55296
	ds_read_b128 v[194:197], v153 offset:56320
	s_add_u32 s78, s42, 0x80
	s_addc_u32 s79, s43, 0
	s_mov_b32 m0, s61
	s_nop 0
	global_load_lds_dwordx4 v149, s[78:79]
	s_mov_b32 m0, s62
	s_nop 0
	global_load_lds_dwordx4 v151, s[78:79]
	s_add_u32 s58, s58, 0x80
	s_addc_u32 s59, s59, 0
	s_mov_b32 m0, s65
	s_nop 0
	global_load_lds_dwordx4 v149, s[58:59]
	s_mov_b32 m0, s66
	s_nop 0
	global_load_lds_dwordx4 v151, s[58:59]
	s_mov_b32 m0, s63
	s_nop 0
	global_load_lds_dwordx4 v148, s[40:41]
	s_mov_b32 m0, s64
	s_nop 0
	global_load_lds_dwordx4 v150, s[40:41]
	s_waitcnt vmcnt(8) lgkmcnt(0)
	s_setprio 1
	s_barrier
	v_mfma_f32_16x16x32_bf16 v[42:45], v[10:13], v[34:37], v[154:157]
	v_mfma_f32_16x16x32_bf16 v[78:81], v[14:17], v[38:41], v[42:45]
	v_mfma_f32_16x16x32_bf16 v[42:45], v[26:29], v[34:37], v[158:161]
	v_mfma_f32_16x16x32_bf16 v[74:77], v[30:33], v[38:41], v[42:45]
	v_mfma_f32_16x16x32_bf16 v[42:45], v[10:13], v[50:53], v[162:165]
	v_mfma_f32_16x16x32_bf16 v[62:65], v[14:17], v[178:181], v[42:45]
	v_mfma_f32_16x16x32_bf16 v[42:45], v[26:29], v[50:53], v[166:169]
	v_mfma_f32_16x16x32_bf16 v[58:61], v[30:33], v[178:181], v[42:45]
	v_mfma_f32_16x16x32_bf16 v[42:45], v[10:13], v[182:185], v[170:173]
	v_mfma_f32_16x16x32_bf16 v[2:5], v[10:13], v[190:193], v[2:5]
	v_mfma_f32_16x16x32_bf16 v[46:49], v[14:17], v[186:189], v[42:45]
	v_mfma_f32_16x16x32_bf16 v[42:45], v[26:29], v[182:185], v[174:177]
	v_mfma_f32_16x16x32_bf16 v[14:17], v[14:17], v[194:197], v[2:5]
	v_mfma_f32_16x16x32_bf16 v[2:5], v[26:29], v[190:193], v[6:9]
	v_mfma_f32_16x16x32_bf16 v[42:45], v[30:33], v[186:189], v[42:45]
	v_mfma_f32_16x16x32_bf16 v[10:13], v[30:33], v[194:197], v[2:5]
	v_mfma_f32_16x16x32_bf16 v[2:5], v[232:235], v[34:37], v[202:205]
	v_mfma_f32_16x16x32_bf16 v[70:73], v[236:239], v[38:41], v[2:5]
	v_mfma_f32_16x16x32_bf16 v[2:5], v[240:243], v[34:37], v[206:209]
	v_mfma_f32_16x16x32_bf16 v[66:69], v[244:247], v[38:41], v[2:5]
	v_mfma_f32_16x16x32_bf16 v[2:5], v[232:235], v[50:53], v[216:219]
	v_mfma_f32_16x16x32_bf16 v[54:57], v[236:239], v[178:181], v[2:5]
	v_mfma_f32_16x16x32_bf16 v[2:5], v[240:243], v[50:53], v[220:223]
	v_mfma_f32_16x16x32_bf16 v[50:53], v[244:247], v[178:181], v[2:5]
	v_mfma_f32_16x16x32_bf16 v[2:5], v[232:235], v[182:185], v[224:227]
	v_mfma_f32_16x16x32_bf16 v[38:41], v[236:239], v[186:189], v[2:5]
	v_mfma_f32_16x16x32_bf16 v[2:5], v[240:243], v[182:185], v[228:231]
	v_mfma_f32_16x16x32_bf16 v[34:37], v[244:247], v[186:189], v[2:5]
	v_mfma_f32_16x16x32_bf16 v[2:5], v[232:235], v[190:193], v[18:21]
	v_mfma_f32_16x16x32_bf16 v[6:9], v[236:239], v[194:197], v[2:5]
	v_mfma_f32_16x16x32_bf16 v[2:5], v[240:243], v[190:193], v[22:25]
	v_mfma_f32_16x16x32_bf16 v[2:5], v[244:247], v[194:197], v[2:5]
	s_setprio 0
	s_barrier
	s_andn2_b64 vcc, exec, s[48:49]
	s_cbranch_vccnz .LBB0_441
	s_barrier

.LBB0_484:
	v_add_u32_e32 v0, 0x10000, v156
	ds_read_b128 v[62:65], v0
	ds_read_b128 v[66:69], v0 offset:1024
	ds_read_b128 v[70:73], v0 offset:2048
	ds_read_b128 v[74:77], v0 offset:3072
	v_add_u32_e32 v0, 0x14000, v156
	ds_read_b128 v[146:149], v0
	ds_read_b128 v[158:161], v0 offset:1024
	ds_read_b128 v[162:165], v0 offset:2048
	ds_read_b128 v[166:169], v0 offset:3072
	s_cmp_eq_u32 s26, 12
	s_cselect_b32 s44, s70, s24
	s_cselect_b32 s45, s71, s25
	s_cselect_b32 s42, s72, s0
	s_cselect_b32 s43, s73, s11
	s_add_u32 s40, s44, 0x80
	s_addc_u32 s41, s45, 0
	ds_read_b128 v[170:173], v157
	ds_read_b128 v[174:177], v157 offset:1024
	ds_read_b128 v[202:205], v157 offset:2048
	ds_read_b128 v[206:209], v157 offset:3072
	ds_read_b128 v[216:219], v157 offset:4096
	ds_read_b128 v[220:223], v157 offset:5120
	ds_read_b128 v[224:227], v157 offset:6144
	ds_read_b128 v[228:231], v157 offset:7168
	s_add_u32 s27, s24, s52
	s_addc_u32 s29, s25, s53
	s_add_u32 s28, s27, 0xffffff80
	s_addc_u32 s29, s29, -1
	s_mov_b32 m0, s68
	s_nop 0
	global_load_lds_dwordx4 v152, s[28:29]
	s_mov_b32 m0, s69
	s_nop 0
	global_load_lds_dwordx4 v154, s[28:29]
	s_waitcnt vmcnt(8) lgkmcnt(0)
	s_setprio 1
	s_barrier
	v_mfma_f32_16x16x32_bf16 v[142:145], v[62:65], v[170:173], v[142:145]
	v_mfma_f32_16x16x32_bf16 v[138:141], v[70:73], v[170:173], v[138:141]
	v_mfma_f32_16x16x32_bf16 v[126:129], v[62:65], v[202:205], v[126:129]
	v_mfma_f32_16x16x32_bf16 v[122:125], v[70:73], v[202:205], v[122:125]
	v_mfma_f32_16x16x32_bf16 v[110:113], v[62:65], v[216:219], v[110:113]
	v_mfma_f32_16x16x32_bf16 v[106:109], v[70:73], v[216:219], v[106:109]
	v_mfma_f32_16x16x32_bf16 v[94:97], v[62:65], v[224:227], v[94:97]
	v_mfma_f32_16x16x32_bf16 v[90:93], v[70:73], v[224:227], v[90:93]
	v_mfma_f32_16x16x32_bf16 v[142:145], v[66:69], v[174:177], v[142:145]
	v_mfma_f32_16x16x32_bf16 v[138:141], v[74:77], v[174:177], v[138:141]
	v_mfma_f32_16x16x32_bf16 v[126:129], v[66:69], v[206:209], v[126:129]
	v_mfma_f32_16x16x32_bf16 v[122:125], v[74:77], v[206:209], v[122:125]
	v_mfma_f32_16x16x32_bf16 v[110:113], v[66:69], v[220:223], v[110:113]
	v_mfma_f32_16x16x32_bf16 v[106:109], v[74:77], v[220:223], v[106:109]
	v_mfma_f32_16x16x32_bf16 v[94:97], v[66:69], v[228:231], v[94:97]
	v_mfma_f32_16x16x32_bf16 v[90:93], v[74:77], v[228:231], v[90:93]
	v_mfma_f32_16x16x32_bf16 v[134:137], v[146:149], v[170:173], v[134:137]
	v_mfma_f32_16x16x32_bf16 v[130:133], v[162:165], v[170:173], v[130:133]
	v_mfma_f32_16x16x32_bf16 v[118:121], v[146:149], v[202:205], v[118:121]
	v_mfma_f32_16x16x32_bf16 v[114:117], v[162:165], v[202:205], v[114:117]
	v_mfma_f32_16x16x32_bf16 v[102:105], v[146:149], v[216:219], v[102:105]
	v_mfma_f32_16x16x32_bf16 v[98:101], v[162:165], v[216:219], v[98:101]
	v_mfma_f32_16x16x32_bf16 v[86:89], v[146:149], v[224:227], v[86:89]
	v_mfma_f32_16x16x32_bf16 v[82:85], v[162:165], v[224:227], v[82:85]
	v_mfma_f32_16x16x32_bf16 v[134:137], v[158:161], v[174:177], v[134:137]
	v_mfma_f32_16x16x32_bf16 v[130:133], v[166:169], v[174:177], v[130:133]
	v_mfma_f32_16x16x32_bf16 v[118:121], v[158:161], v[206:209], v[118:121]
	v_mfma_f32_16x16x32_bf16 v[114:117], v[166:169], v[206:209], v[114:117]
	v_mfma_f32_16x16x32_bf16 v[102:105], v[158:161], v[220:223], v[102:105]
	v_mfma_f32_16x16x32_bf16 v[98:101], v[166:169], v[220:223], v[98:101]
	v_mfma_f32_16x16x32_bf16 v[86:89], v[158:161], v[228:231], v[86:89]
	v_mfma_f32_16x16x32_bf16 v[82:85], v[166:169], v[228:231], v[82:85]
	s_setprio 0
	s_barrier
	ds_read_b128 v[170:173], v157 offset:16384
	ds_read_b128 v[174:177], v157 offset:17408
	ds_read_b128 v[202:205], v157 offset:18432
	ds_read_b128 v[206:209], v157 offset:19456
	ds_read_b128 v[216:219], v157 offset:20480
	ds_read_b128 v[220:223], v157 offset:21504
	ds_read_b128 v[224:227], v157 offset:22528
	ds_read_b128 v[228:231], v157 offset:23552
	s_mov_b32 m0, s65
	s_nop 0
	global_load_lds_dwordx4 v153, s[42:43]
	s_mov_b32 m0, s22
	s_nop 0
	global_load_lds_dwordx4 v155, s[42:43]
	s_add_u32 s46, s42, s56
	s_addc_u32 s47, s43, s57
	s_mov_b32 m0, s23
	s_nop 0
	global_load_lds_dwordx4 v153, s[46:47]
	s_mov_b32 m0, s50
	s_nop 0
	global_load_lds_dwordx4 v155, s[46:47]
	s_nop 0
	s_mov_b32 m0, s64
	s_nop 0
	global_load_lds_dwordx4 v152, s[44:45]
	s_mov_b32 m0, s51
	s_nop 0
	global_load_lds_dwordx4 v154, s[44:45]
	s_waitcnt vmcnt(8) lgkmcnt(0)
	s_setprio 1
	s_barrier
	v_mfma_f32_16x16x32_bf16 v[78:81], v[62:65], v[170:173], v[78:81]
	v_mfma_f32_16x16x32_bf16 v[58:61], v[70:73], v[170:173], v[58:61]
	v_mfma_f32_16x16x32_bf16 v[46:49], v[62:65], v[202:205], v[46:49]
	v_mfma_f32_16x16x32_bf16 v[42:45], v[70:73], v[202:205], v[42:45]
	v_mfma_f32_16x16x32_bf16 v[30:33], v[62:65], v[216:219], v[30:33]
	v_mfma_f32_16x16x32_bf16 v[26:29], v[70:73], v[216:219], v[26:29]
	v_mfma_f32_16x16x32_bf16 v[14:17], v[62:65], v[224:227], v[14:17]
	v_mfma_f32_16x16x32_bf16 v[10:13], v[70:73], v[224:227], v[10:13]
	v_mfma_f32_16x16x32_bf16 v[78:81], v[66:69], v[174:177], v[78:81]
	v_mfma_f32_16x16x32_bf16 v[58:61], v[74:77], v[174:177], v[58:61]
	v_mfma_f32_16x16x32_bf16 v[46:49], v[66:69], v[206:209], v[46:49]
	v_mfma_f32_16x16x32_bf16 v[42:45], v[74:77], v[206:209], v[42:45]
	v_mfma_f32_16x16x32_bf16 v[30:33], v[66:69], v[220:223], v[30:33]
	v_mfma_f32_16x16x32_bf16 v[26:29], v[74:77], v[220:223], v[26:29]
	v_mfma_f32_16x16x32_bf16 v[14:17], v[66:69], v[228:231], v[14:17]
	v_mfma_f32_16x16x32_bf16 v[10:13], v[74:77], v[228:231], v[10:13]
	v_mfma_f32_16x16x32_bf16 v[54:57], v[146:149], v[170:173], v[54:57]
	v_mfma_f32_16x16x32_bf16 v[50:53], v[162:165], v[170:173], v[50:53]
	v_mfma_f32_16x16x32_bf16 v[38:41], v[146:149], v[202:205], v[38:41]
	v_mfma_f32_16x16x32_bf16 v[34:37], v[162:165], v[202:205], v[34:37]
	v_mfma_f32_16x16x32_bf16 v[22:25], v[146:149], v[216:219], v[22:25]
	v_mfma_f32_16x16x32_bf16 v[18:21], v[162:165], v[216:219], v[18:21]
	v_mfma_f32_16x16x32_bf16 v[6:9], v[146:149], v[224:227], v[6:9]
	v_mfma_f32_16x16x32_bf16 v[2:5], v[162:165], v[224:227], v[2:5]
	v_mfma_f32_16x16x32_bf16 v[54:57], v[158:161], v[174:177], v[54:57]
	v_mfma_f32_16x16x32_bf16 v[50:53], v[166:169], v[174:177], v[50:53]
	v_mfma_f32_16x16x32_bf16 v[38:41], v[158:161], v[206:209], v[38:41]
	v_mfma_f32_16x16x32_bf16 v[34:37], v[166:169], v[206:209], v[34:37]
	v_mfma_f32_16x16x32_bf16 v[22:25], v[158:161], v[220:223], v[22:25]
	v_mfma_f32_16x16x32_bf16 v[18:21], v[166:169], v[220:223], v[18:21]
	v_mfma_f32_16x16x32_bf16 v[6:9], v[158:161], v[228:231], v[6:9]
	v_mfma_f32_16x16x32_bf16 v[2:5], v[166:169], v[228:231], v[2:5]
	s_setprio 0
	s_barrier
	v_add_u32_e32 v0, 0x18000, v156
	ds_read_b128 v[62:65], v0
	ds_read_b128 v[66:69], v0 offset:1024
	ds_read_b128 v[70:73], v0 offset:2048
	ds_read_b128 v[74:77], v0 offset:3072
	v_add_u32_e32 v0, 0x1c000, v156
	ds_read_b128 v[146:149], v0
	ds_read_b128 v[158:161], v0 offset:1024
	ds_read_b128 v[162:165], v0 offset:2048
	ds_read_b128 v[166:169], v0 offset:3072
	ds_read_b128 v[170:173], v157 offset:32768
	ds_read_b128 v[174:177], v157 offset:33792
	ds_read_b128 v[202:205], v157 offset:34816
	ds_read_b128 v[206:209], v157 offset:35840
	ds_read_b128 v[216:219], v157 offset:36864
	ds_read_b128 v[220:223], v157 offset:37888
	ds_read_b128 v[224:227], v157 offset:38912
	ds_read_b128 v[228:231], v157 offset:39936
	s_add_u32 s28, s44, s52
	s_addc_u32 s29, s45, s53
	s_mov_b32 m0, s60
	s_nop 0
	global_load_lds_dwordx4 v152, s[28:29]
	s_mov_b32 m0, s61
	s_nop 0
	global_load_lds_dwordx4 v154, s[28:29]
	s_waitcnt vmcnt(8) lgkmcnt(0)
	s_setprio 1
	s_barrier
	v_mfma_f32_16x16x32_bf16 v[142:145], v[62:65], v[170:173], v[142:145]
	v_mfma_f32_16x16x32_bf16 v[138:141], v[70:73], v[170:173], v[138:141]
	v_mfma_f32_16x16x32_bf16 v[126:129], v[62:65], v[202:205], v[126:129]
	v_mfma_f32_16x16x32_bf16 v[122:125], v[70:73], v[202:205], v[122:125]
	v_mfma_f32_16x16x32_bf16 v[110:113], v[62:65], v[216:219], v[110:113]
	v_mfma_f32_16x16x32_bf16 v[106:109], v[70:73], v[216:219], v[106:109]
	v_mfma_f32_16x16x32_bf16 v[94:97], v[62:65], v[224:227], v[94:97]
	v_mfma_f32_16x16x32_bf16 v[90:93], v[70:73], v[224:227], v[90:93]
	v_mfma_f32_16x16x32_bf16 v[142:145], v[66:69], v[174:177], v[142:145]
	v_mfma_f32_16x16x32_bf16 v[138:141], v[74:77], v[174:177], v[138:141]
	v_mfma_f32_16x16x32_bf16 v[126:129], v[66:69], v[206:209], v[126:129]
	v_mfma_f32_16x16x32_bf16 v[122:125], v[74:77], v[206:209], v[122:125]
	v_mfma_f32_16x16x32_bf16 v[110:113], v[66:69], v[220:223], v[110:113]
	v_mfma_f32_16x16x32_bf16 v[106:109], v[74:77], v[220:223], v[106:109]
	v_mfma_f32_16x16x32_bf16 v[94:97], v[66:69], v[228:231], v[94:97]
	v_mfma_f32_16x16x32_bf16 v[90:93], v[74:77], v[228:231], v[90:93]
	v_mfma_f32_16x16x32_bf16 v[134:137], v[146:149], v[170:173], v[134:137]
	v_mfma_f32_16x16x32_bf16 v[130:133], v[162:165], v[170:173], v[130:133]
	v_mfma_f32_16x16x32_bf16 v[118:121], v[146:149], v[202:205], v[118:121]
	v_mfma_f32_16x16x32_bf16 v[114:117], v[162:165], v[202:205], v[114:117]
	v_mfma_f32_16x16x32_bf16 v[102:105], v[146:149], v[216:219], v[102:105]
	v_mfma_f32_16x16x32_bf16 v[98:101], v[162:165], v[216:219], v[98:101]
	v_mfma_f32_16x16x32_bf16 v[86:89], v[146:149], v[224:227], v[86:89]
	v_mfma_f32_16x16x32_bf16 v[82:85], v[162:165], v[224:227], v[82:85]
	v_mfma_f32_16x16x32_bf16 v[134:137], v[158:161], v[174:177], v[134:137]
	v_mfma_f32_16x16x32_bf16 v[130:133], v[166:169], v[174:177], v[130:133]
	v_mfma_f32_16x16x32_bf16 v[118:121], v[158:161], v[206:209], v[118:121]
	v_mfma_f32_16x16x32_bf16 v[114:117], v[166:169], v[206:209], v[114:117]
	v_mfma_f32_16x16x32_bf16 v[102:105], v[158:161], v[220:223], v[102:105]
	v_mfma_f32_16x16x32_bf16 v[98:101], v[166:169], v[220:223], v[98:101]
	v_mfma_f32_16x16x32_bf16 v[86:89], v[158:161], v[228:231], v[86:89]
	v_mfma_f32_16x16x32_bf16 v[82:85], v[166:169], v[228:231], v[82:85]
	s_setprio 0
	s_barrier
	ds_read_b128 v[170:173], v157 offset:49152
	ds_read_b128 v[174:177], v157 offset:50176
	ds_read_b128 v[202:205], v157 offset:51200
	ds_read_b128 v[206:209], v157 offset:52224
	ds_read_b128 v[216:219], v157 offset:53248
	ds_read_b128 v[220:223], v157 offset:54272
	ds_read_b128 v[224:227], v157 offset:55296
	ds_read_b128 v[228:231], v157 offset:56320
	s_add_u32 s28, s42, 0x80
	s_addc_u32 s29, s43, 0
	s_mov_b32 m0, s66
	s_nop 0
	global_load_lds_dwordx4 v153, s[28:29]
	s_mov_b32 m0, s67
	s_nop 0
	global_load_lds_dwordx4 v155, s[28:29]
	s_add_u32 s28, s46, 0x80
	s_addc_u32 s29, s47, 0
	s_mov_b32 m0, s7
	s_nop 0
	global_load_lds_dwordx4 v153, s[28:29]
	s_mov_b32 m0, s91
	s_nop 0
	global_load_lds_dwordx4 v155, s[28:29]
	s_nop 0
	s_mov_b32 m0, s97
	s_nop 0
	global_load_lds_dwordx4 v152, s[40:41]
	s_mov_b32 m0, s6
	s_nop 0
	global_load_lds_dwordx4 v154, s[40:41]
	s_waitcnt vmcnt(8) lgkmcnt(0)
	s_setprio 1
	s_barrier
	v_mfma_f32_16x16x32_bf16 v[78:81], v[62:65], v[170:173], v[78:81]
	v_mfma_f32_16x16x32_bf16 v[58:61], v[70:73], v[170:173], v[58:61]
	v_mfma_f32_16x16x32_bf16 v[46:49], v[62:65], v[202:205], v[46:49]
	v_mfma_f32_16x16x32_bf16 v[42:45], v[70:73], v[202:205], v[42:45]
	v_mfma_f32_16x16x32_bf16 v[30:33], v[62:65], v[216:219], v[30:33]
	v_mfma_f32_16x16x32_bf16 v[26:29], v[70:73], v[216:219], v[26:29]
	v_mfma_f32_16x16x32_bf16 v[14:17], v[62:65], v[224:227], v[14:17]
	v_mfma_f32_16x16x32_bf16 v[10:13], v[70:73], v[224:227], v[10:13]
	v_mfma_f32_16x16x32_bf16 v[78:81], v[66:69], v[174:177], v[78:81]
	v_mfma_f32_16x16x32_bf16 v[58:61], v[74:77], v[174:177], v[58:61]
	v_mfma_f32_16x16x32_bf16 v[46:49], v[66:69], v[206:209], v[46:49]
	v_mfma_f32_16x16x32_bf16 v[42:45], v[74:77], v[206:209], v[42:45]
	v_mfma_f32_16x16x32_bf16 v[30:33], v[66:69], v[220:223], v[30:33]
	v_mfma_f32_16x16x32_bf16 v[26:29], v[74:77], v[220:223], v[26:29]
	v_mfma_f32_16x16x32_bf16 v[14:17], v[66:69], v[228:231], v[14:17]
	v_mfma_f32_16x16x32_bf16 v[10:13], v[74:77], v[228:231], v[10:13]
	v_mfma_f32_16x16x32_bf16 v[54:57], v[146:149], v[170:173], v[54:57]
	v_mfma_f32_16x16x32_bf16 v[50:53], v[162:165], v[170:173], v[50:53]
	v_mfma_f32_16x16x32_bf16 v[38:41], v[146:149], v[202:205], v[38:41]
	v_mfma_f32_16x16x32_bf16 v[34:37], v[162:165], v[202:205], v[34:37]
	v_mfma_f32_16x16x32_bf16 v[22:25], v[146:149], v[216:219], v[22:25]
	v_mfma_f32_16x16x32_bf16 v[18:21], v[162:165], v[216:219], v[18:21]
	v_mfma_f32_16x16x32_bf16 v[6:9], v[146:149], v[224:227], v[6:9]
	v_mfma_f32_16x16x32_bf16 v[2:5], v[162:165], v[224:227], v[2:5]
	v_mfma_f32_16x16x32_bf16 v[54:57], v[158:161], v[174:177], v[54:57]
	v_mfma_f32_16x16x32_bf16 v[50:53], v[166:169], v[174:177], v[50:53]
	v_mfma_f32_16x16x32_bf16 v[38:41], v[158:161], v[206:209], v[38:41]
	v_mfma_f32_16x16x32_bf16 v[34:37], v[166:169], v[206:209], v[34:37]
	v_mfma_f32_16x16x32_bf16 v[22:25], v[158:161], v[220:223], v[22:25]
	v_mfma_f32_16x16x32_bf16 v[18:21], v[166:169], v[220:223], v[18:21]
	v_mfma_f32_16x16x32_bf16 v[6:9], v[158:161], v[228:231], v[6:9]
	v_mfma_f32_16x16x32_bf16 v[2:5], v[166:169], v[228:231], v[2:5]
	s_setprio 0
	s_barrier
	s_add_i32 s26, s26, 2
	s_add_u32 s0, s0, 0x100
	s_addc_u32 s11, s11, 0
	s_add_u32 s24, s24, 0x100
	s_addc_u32 s25, s25, 0
	s_cmp_gt_u32 s26, 13
	s_cbranch_scc0 .LBB0_484
	v_readlane_b32 s24, v255, 14
	v_readlane_b32 s25, v255, 15
	s_and_b64 vcc, exec, s[24:25]
	s_cbranch_vccz .LBB0_487
	s_barrier

.LBB0_608:
	v_add_u32_e32 v135, 0x10000, v133
	ds_read_b128 v[136:139], v135
	ds_read_b128 v[140:143], v135 offset:1024
	ds_read_b128 v[144:147], v135 offset:2048
	ds_read_b128 v[148:151], v135 offset:3072
	v_add_u32_e32 v135, 0x14000, v133
	ds_read_b128 v[152:155], v135
	ds_read_b128 v[156:159], v135 offset:1024
	ds_read_b128 v[160:163], v135 offset:2048
	ds_read_b128 v[164:167], v135 offset:3072
	s_cmp_eq_u32 s81, 12
	s_cselect_b32 s58, s52, s79
	s_cselect_b32 s59, s53, s80
	s_cselect_b32 s56, s40, s11
	s_cselect_b32 s57, s41, s45
	s_add_u32 s54, s58, 0x80
	s_addc_u32 s55, s59, 0
	ds_read_b128 v[168:171], v134
	ds_read_b128 v[172:175], v134 offset:1024
	ds_read_b128 v[176:179], v134 offset:2048
	ds_read_b128 v[202:205], v134 offset:3072
	ds_read_b128 v[206:209], v134 offset:4096
	ds_read_b128 v[216:219], v134 offset:5120
	ds_read_b128 v[220:223], v134 offset:6144
	ds_read_b128 v[224:227], v134 offset:7168
	s_add_u32 s60, s79, s6
	s_addc_u32 s61, s80, s7
	s_add_u32 s60, s60, 0xffffff80
	s_addc_u32 s61, s61, -1
	s_mov_b32 m0, s69
	s_nop 0
	global_load_lds_dwordx4 v0, s[60:61]
	s_mov_b32 m0, s70
	s_nop 0
	global_load_lds_dwordx4 v131, s[60:61]
	s_waitcnt vmcnt(8) lgkmcnt(0)
	s_setprio 1
	s_barrier
	v_mfma_f32_16x16x32_bf16 v[126:129], v[136:139], v[168:171], v[126:129]
	v_mfma_f32_16x16x32_bf16 v[122:125], v[144:147], v[168:171], v[122:125]
	v_mfma_f32_16x16x32_bf16 v[118:121], v[136:139], v[176:179], v[118:121]
	v_mfma_f32_16x16x32_bf16 v[114:117], v[144:147], v[176:179], v[114:117]
	v_mfma_f32_16x16x32_bf16 v[106:109], v[136:139], v[206:209], v[106:109]
	v_mfma_f32_16x16x32_bf16 v[98:101], v[144:147], v[206:209], v[98:101]
	v_mfma_f32_16x16x32_bf16 v[90:93], v[136:139], v[220:223], v[90:93]
	v_mfma_f32_16x16x32_bf16 v[82:85], v[144:147], v[220:223], v[82:85]
	v_mfma_f32_16x16x32_bf16 v[126:129], v[140:143], v[172:175], v[126:129]
	v_mfma_f32_16x16x32_bf16 v[122:125], v[148:151], v[172:175], v[122:125]
	v_mfma_f32_16x16x32_bf16 v[118:121], v[140:143], v[202:205], v[118:121]
	v_mfma_f32_16x16x32_bf16 v[114:117], v[148:151], v[202:205], v[114:117]
	v_mfma_f32_16x16x32_bf16 v[106:109], v[140:143], v[216:219], v[106:109]
	v_mfma_f32_16x16x32_bf16 v[98:101], v[148:151], v[216:219], v[98:101]
	v_mfma_f32_16x16x32_bf16 v[90:93], v[140:143], v[224:227], v[90:93]
	v_mfma_f32_16x16x32_bf16 v[82:85], v[148:151], v[224:227], v[82:85]
	v_mfma_f32_16x16x32_bf16 v[110:113], v[152:155], v[168:171], v[110:113]
	v_mfma_f32_16x16x32_bf16 v[102:105], v[160:163], v[168:171], v[102:105]
	v_mfma_f32_16x16x32_bf16 v[94:97], v[152:155], v[176:179], v[94:97]
	v_mfma_f32_16x16x32_bf16 v[86:89], v[160:163], v[176:179], v[86:89]
	v_mfma_f32_16x16x32_bf16 v[78:81], v[152:155], v[206:209], v[78:81]
	v_mfma_f32_16x16x32_bf16 v[74:77], v[160:163], v[206:209], v[74:77]
	v_mfma_f32_16x16x32_bf16 v[70:73], v[152:155], v[220:223], v[70:73]
	v_mfma_f32_16x16x32_bf16 v[66:69], v[160:163], v[220:223], v[66:69]
	v_mfma_f32_16x16x32_bf16 v[110:113], v[156:159], v[172:175], v[110:113]
	v_mfma_f32_16x16x32_bf16 v[102:105], v[164:167], v[172:175], v[102:105]
	v_mfma_f32_16x16x32_bf16 v[94:97], v[156:159], v[202:205], v[94:97]
	v_mfma_f32_16x16x32_bf16 v[86:89], v[164:167], v[202:205], v[86:89]
	v_mfma_f32_16x16x32_bf16 v[78:81], v[156:159], v[216:219], v[78:81]
	v_mfma_f32_16x16x32_bf16 v[74:77], v[164:167], v[216:219], v[74:77]
	v_mfma_f32_16x16x32_bf16 v[70:73], v[156:159], v[224:227], v[70:73]
	v_mfma_f32_16x16x32_bf16 v[66:69], v[164:167], v[224:227], v[66:69]
	s_setprio 0
	s_barrier
	ds_read_b128 v[168:171], v134 offset:16384
	ds_read_b128 v[172:175], v134 offset:17408
	ds_read_b128 v[176:179], v134 offset:18432
	ds_read_b128 v[202:205], v134 offset:19456
	ds_read_b128 v[206:209], v134 offset:20480
	ds_read_b128 v[216:219], v134 offset:21504
	ds_read_b128 v[220:223], v134 offset:22528
	ds_read_b128 v[224:227], v134 offset:23552
	s_mov_b32 m0, s25
	s_nop 0
	global_load_lds_dwordx4 v130, s[56:57]
	s_mov_b32 m0, s26
	s_nop 0
	global_load_lds_dwordx4 v132, s[56:57]
	s_add_u32 s60, s56, s22
	s_addc_u32 s61, s57, s23
	s_mov_b32 m0, s27
	s_nop 0
	global_load_lds_dwordx4 v130, s[60:61]
	s_mov_b32 m0, s28
	s_nop 0
	global_load_lds_dwordx4 v132, s[60:61]
	s_nop 0
	s_mov_b32 m0, s24
	s_nop 0
	global_load_lds_dwordx4 v0, s[58:59]
	s_mov_b32 m0, s29
	s_nop 0
	global_load_lds_dwordx4 v131, s[58:59]
	s_waitcnt vmcnt(8) lgkmcnt(0)
	s_setprio 1
	s_barrier
	v_mfma_f32_16x16x32_bf16 v[62:65], v[136:139], v[168:171], v[62:65]
	v_mfma_f32_16x16x32_bf16 v[58:61], v[144:147], v[168:171], v[58:61]
	v_mfma_f32_16x16x32_bf16 v[54:57], v[136:139], v[176:179], v[54:57]
	v_mfma_f32_16x16x32_bf16 v[50:53], v[144:147], v[176:179], v[50:53]
	v_mfma_f32_16x16x32_bf16 v[38:41], v[136:139], v[206:209], v[38:41]
	v_mfma_f32_16x16x32_bf16 v[34:37], v[144:147], v[206:209], v[34:37]
	v_mfma_f32_16x16x32_bf16 v[22:25], v[136:139], v[220:223], v[22:25]
	v_mfma_f32_16x16x32_bf16 v[18:21], v[144:147], v[220:223], v[18:21]
	v_mfma_f32_16x16x32_bf16 v[62:65], v[140:143], v[172:175], v[62:65]
	v_mfma_f32_16x16x32_bf16 v[58:61], v[148:151], v[172:175], v[58:61]
	v_mfma_f32_16x16x32_bf16 v[54:57], v[140:143], v[202:205], v[54:57]
	v_mfma_f32_16x16x32_bf16 v[50:53], v[148:151], v[202:205], v[50:53]
	v_mfma_f32_16x16x32_bf16 v[38:41], v[140:143], v[216:219], v[38:41]
	v_mfma_f32_16x16x32_bf16 v[34:37], v[148:151], v[216:219], v[34:37]
	v_mfma_f32_16x16x32_bf16 v[22:25], v[140:143], v[224:227], v[22:25]
	v_mfma_f32_16x16x32_bf16 v[18:21], v[148:151], v[224:227], v[18:21]
	v_mfma_f32_16x16x32_bf16 v[46:49], v[152:155], v[168:171], v[46:49]
	v_mfma_f32_16x16x32_bf16 v[42:45], v[160:163], v[168:171], v[42:45]
	v_mfma_f32_16x16x32_bf16 v[30:33], v[152:155], v[176:179], v[30:33]
	v_mfma_f32_16x16x32_bf16 v[26:29], v[160:163], v[176:179], v[26:29]
	v_mfma_f32_16x16x32_bf16 v[14:17], v[152:155], v[206:209], v[14:17]
	v_mfma_f32_16x16x32_bf16 v[10:13], v[160:163], v[206:209], v[10:13]
	v_mfma_f32_16x16x32_bf16 v[6:9], v[152:155], v[220:223], v[6:9]
	v_mfma_f32_16x16x32_bf16 v[2:5], v[160:163], v[220:223], v[2:5]
	v_mfma_f32_16x16x32_bf16 v[46:49], v[156:159], v[172:175], v[46:49]
	v_mfma_f32_16x16x32_bf16 v[42:45], v[164:167], v[172:175], v[42:45]
	v_mfma_f32_16x16x32_bf16 v[30:33], v[156:159], v[202:205], v[30:33]
	v_mfma_f32_16x16x32_bf16 v[26:29], v[164:167], v[202:205], v[26:29]
	v_mfma_f32_16x16x32_bf16 v[14:17], v[156:159], v[216:219], v[14:17]
	v_mfma_f32_16x16x32_bf16 v[10:13], v[164:167], v[216:219], v[10:13]
	v_mfma_f32_16x16x32_bf16 v[6:9], v[156:159], v[224:227], v[6:9]
	v_mfma_f32_16x16x32_bf16 v[2:5], v[164:167], v[224:227], v[2:5]
	s_setprio 0
	s_barrier
	v_add_u32_e32 v135, 0x18000, v133
	ds_read_b128 v[136:139], v135
	ds_read_b128 v[140:143], v135 offset:1024
	ds_read_b128 v[144:147], v135 offset:2048
	ds_read_b128 v[148:151], v135 offset:3072
	v_add_u32_e32 v135, 0x1c000, v133
	ds_read_b128 v[152:155], v135
	ds_read_b128 v[156:159], v135 offset:1024
	ds_read_b128 v[160:163], v135 offset:2048
	ds_read_b128 v[164:167], v135 offset:3072
	ds_read_b128 v[168:171], v134 offset:32768
	ds_read_b128 v[172:175], v134 offset:33792
	ds_read_b128 v[176:179], v134 offset:34816
	ds_read_b128 v[202:205], v134 offset:35840
	ds_read_b128 v[206:209], v134 offset:36864
	ds_read_b128 v[216:219], v134 offset:37888
	ds_read_b128 v[220:223], v134 offset:38912
	ds_read_b128 v[224:227], v134 offset:39936
	s_add_u32 s58, s58, s6
	s_addc_u32 s59, s59, s7
	s_mov_b32 m0, s30
	s_nop 0
	global_load_lds_dwordx4 v0, s[58:59]
	s_mov_b32 m0, s31
	s_nop 0
	global_load_lds_dwordx4 v131, s[58:59]
	s_waitcnt vmcnt(8) lgkmcnt(0)
	s_setprio 1
	s_barrier
	v_mfma_f32_16x16x32_bf16 v[126:129], v[136:139], v[168:171], v[126:129]
	v_mfma_f32_16x16x32_bf16 v[122:125], v[144:147], v[168:171], v[122:125]
	v_mfma_f32_16x16x32_bf16 v[118:121], v[136:139], v[176:179], v[118:121]
	v_mfma_f32_16x16x32_bf16 v[114:117], v[144:147], v[176:179], v[114:117]
	v_mfma_f32_16x16x32_bf16 v[106:109], v[136:139], v[206:209], v[106:109]
	v_mfma_f32_16x16x32_bf16 v[98:101], v[144:147], v[206:209], v[98:101]
	v_mfma_f32_16x16x32_bf16 v[90:93], v[136:139], v[220:223], v[90:93]
	v_mfma_f32_16x16x32_bf16 v[82:85], v[144:147], v[220:223], v[82:85]
	v_mfma_f32_16x16x32_bf16 v[126:129], v[140:143], v[172:175], v[126:129]
	v_mfma_f32_16x16x32_bf16 v[122:125], v[148:151], v[172:175], v[122:125]
	v_mfma_f32_16x16x32_bf16 v[118:121], v[140:143], v[202:205], v[118:121]
	v_mfma_f32_16x16x32_bf16 v[114:117], v[148:151], v[202:205], v[114:117]
	v_mfma_f32_16x16x32_bf16 v[106:109], v[140:143], v[216:219], v[106:109]
	v_mfma_f32_16x16x32_bf16 v[98:101], v[148:151], v[216:219], v[98:101]
	v_mfma_f32_16x16x32_bf16 v[90:93], v[140:143], v[224:227], v[90:93]
	v_mfma_f32_16x16x32_bf16 v[82:85], v[148:151], v[224:227], v[82:85]
	v_mfma_f32_16x16x32_bf16 v[110:113], v[152:155], v[168:171], v[110:113]
	v_mfma_f32_16x16x32_bf16 v[102:105], v[160:163], v[168:171], v[102:105]
	v_mfma_f32_16x16x32_bf16 v[94:97], v[152:155], v[176:179], v[94:97]
	v_mfma_f32_16x16x32_bf16 v[86:89], v[160:163], v[176:179], v[86:89]
	v_mfma_f32_16x16x32_bf16 v[78:81], v[152:155], v[206:209], v[78:81]
	v_mfma_f32_16x16x32_bf16 v[74:77], v[160:163], v[206:209], v[74:77]
	v_mfma_f32_16x16x32_bf16 v[70:73], v[152:155], v[220:223], v[70:73]
	v_mfma_f32_16x16x32_bf16 v[66:69], v[160:163], v[220:223], v[66:69]
	v_mfma_f32_16x16x32_bf16 v[110:113], v[156:159], v[172:175], v[110:113]
	v_mfma_f32_16x16x32_bf16 v[102:105], v[164:167], v[172:175], v[102:105]
	v_mfma_f32_16x16x32_bf16 v[94:97], v[156:159], v[202:205], v[94:97]
	v_mfma_f32_16x16x32_bf16 v[86:89], v[164:167], v[202:205], v[86:89]
	v_mfma_f32_16x16x32_bf16 v[78:81], v[156:159], v[216:219], v[78:81]
	v_mfma_f32_16x16x32_bf16 v[74:77], v[164:167], v[216:219], v[74:77]
	v_mfma_f32_16x16x32_bf16 v[70:73], v[156:159], v[224:227], v[70:73]
	v_mfma_f32_16x16x32_bf16 v[66:69], v[164:167], v[224:227], v[66:69]
	s_setprio 0
	s_barrier
	ds_read_b128 v[168:171], v134 offset:49152
	ds_read_b128 v[172:175], v134 offset:50176
	ds_read_b128 v[176:179], v134 offset:51200
	ds_read_b128 v[202:205], v134 offset:52224
	ds_read_b128 v[206:209], v134 offset:53248
	ds_read_b128 v[216:219], v134 offset:54272
	ds_read_b128 v[220:223], v134 offset:55296
	ds_read_b128 v[224:227], v134 offset:56320
	s_add_u32 s56, s56, 0x80
	s_addc_u32 s57, s57, 0
	s_mov_b32 m0, s63
	s_nop 0
	global_load_lds_dwordx4 v130, s[56:57]
	s_mov_b32 m0, s64
	s_nop 0
	global_load_lds_dwordx4 v132, s[56:57]
	s_add_u32 s56, s60, 0x80
	s_addc_u32 s57, s61, 0
	s_mov_b32 m0, s67
	s_nop 0
	global_load_lds_dwordx4 v130, s[56:57]
	s_mov_b32 m0, s68
	s_nop 0
	global_load_lds_dwordx4 v132, s[56:57]
	s_mov_b32 m0, s65
	s_nop 0
	global_load_lds_dwordx4 v0, s[54:55]
	s_mov_b32 m0, s66
	s_nop 0
	global_load_lds_dwordx4 v131, s[54:55]
	s_waitcnt vmcnt(8) lgkmcnt(0)
	s_setprio 1
	s_barrier
	v_mfma_f32_16x16x32_bf16 v[62:65], v[136:139], v[168:171], v[62:65]
	v_mfma_f32_16x16x32_bf16 v[58:61], v[144:147], v[168:171], v[58:61]
	v_mfma_f32_16x16x32_bf16 v[54:57], v[136:139], v[176:179], v[54:57]
	v_mfma_f32_16x16x32_bf16 v[50:53], v[144:147], v[176:179], v[50:53]
	v_mfma_f32_16x16x32_bf16 v[38:41], v[136:139], v[206:209], v[38:41]
	v_mfma_f32_16x16x32_bf16 v[34:37], v[144:147], v[206:209], v[34:37]
	v_mfma_f32_16x16x32_bf16 v[22:25], v[136:139], v[220:223], v[22:25]
	v_mfma_f32_16x16x32_bf16 v[18:21], v[144:147], v[220:223], v[18:21]
	v_mfma_f32_16x16x32_bf16 v[62:65], v[140:143], v[172:175], v[62:65]
	v_mfma_f32_16x16x32_bf16 v[58:61], v[148:151], v[172:175], v[58:61]
	v_mfma_f32_16x16x32_bf16 v[54:57], v[140:143], v[202:205], v[54:57]
	v_mfma_f32_16x16x32_bf16 v[50:53], v[148:151], v[202:205], v[50:53]
	v_mfma_f32_16x16x32_bf16 v[38:41], v[140:143], v[216:219], v[38:41]
	v_mfma_f32_16x16x32_bf16 v[34:37], v[148:151], v[216:219], v[34:37]
	v_mfma_f32_16x16x32_bf16 v[22:25], v[140:143], v[224:227], v[22:25]
	v_mfma_f32_16x16x32_bf16 v[18:21], v[148:151], v[224:227], v[18:21]
	v_mfma_f32_16x16x32_bf16 v[46:49], v[152:155], v[168:171], v[46:49]
	v_mfma_f32_16x16x32_bf16 v[42:45], v[160:163], v[168:171], v[42:45]
	v_mfma_f32_16x16x32_bf16 v[30:33], v[152:155], v[176:179], v[30:33]
	v_mfma_f32_16x16x32_bf16 v[26:29], v[160:163], v[176:179], v[26:29]
	v_mfma_f32_16x16x32_bf16 v[14:17], v[152:155], v[206:209], v[14:17]
	v_mfma_f32_16x16x32_bf16 v[10:13], v[160:163], v[206:209], v[10:13]
	v_mfma_f32_16x16x32_bf16 v[6:9], v[152:155], v[220:223], v[6:9]
	v_mfma_f32_16x16x32_bf16 v[2:5], v[160:163], v[220:223], v[2:5]
	v_mfma_f32_16x16x32_bf16 v[46:49], v[156:159], v[172:175], v[46:49]
	v_mfma_f32_16x16x32_bf16 v[42:45], v[164:167], v[172:175], v[42:45]
	v_mfma_f32_16x16x32_bf16 v[30:33], v[156:159], v[202:205], v[30:33]
	v_mfma_f32_16x16x32_bf16 v[26:29], v[164:167], v[202:205], v[26:29]
	v_mfma_f32_16x16x32_bf16 v[14:17], v[156:159], v[216:219], v[14:17]
	v_mfma_f32_16x16x32_bf16 v[10:13], v[164:167], v[216:219], v[10:13]
	v_mfma_f32_16x16x32_bf16 v[6:9], v[156:159], v[224:227], v[6:9]
	v_mfma_f32_16x16x32_bf16 v[2:5], v[164:167], v[224:227], v[2:5]
	s_setprio 0
	s_barrier
	s_add_i32 s81, s81, 2
	s_add_u32 s11, s11, 0x100
	s_addc_u32 s45, s45, 0
	s_add_u32 s79, s79, 0x100
	s_addc_u32 s80, s80, 0
	s_cmp_gt_u32 s81, 13
	s_cbranch_scc0 .LBB0_608
	s_and_b64 vcc, exec, s[50:51]
	s_cbranch_vccz .LBB0_611
	s_barrier

.LBB0_645:
	s_add_u32 s26, s76, s42
	v_add_u32_e32 v0, 0x10000, v219
	s_addc_u32 s27, s24, s43
	ds_read_b128 v[130:133], v0
	ds_read_b128 v[134:137], v0 offset:1024
	ds_read_b128 v[138:141], v0 offset:2048
	ds_read_b128 v[142:145], v0 offset:3072
	v_add_u32_e32 v0, 0x14000, v219
	s_add_u32 s59, s54, s42
	ds_read_b128 v[146:149], v0
	ds_read_b128 v[150:153], v0 offset:1024
	ds_read_b128 v[154:157], v0 offset:2048
	ds_read_b128 v[158:161], v0 offset:3072
	s_addc_u32 s62, s55, s43
	s_add_u32 s59, s59, 0x100
	s_addc_u32 s62, s62, 0
	s_cmp_eq_u32 s25, 40
	s_cselect_b32 s66, s56, s26
	s_cselect_b32 s67, s57, s27
	s_cselect_b32 s64, s60, s59
	s_cselect_b32 s65, s61, s62
	s_add_u32 s62, s66, 0x80
	s_addc_u32 s63, s67, 0
	ds_read_b128 v[162:165], v220
	ds_read_b128 v[166:169], v220 offset:1024
	ds_read_b128 v[170:173], v220 offset:2048
	ds_read_b128 v[174:177], v220 offset:3072
	ds_read_b128 v[178:181], v220 offset:4096
	ds_read_b128 v[182:185], v220 offset:5120
	ds_read_b128 v[186:189], v220 offset:6144
	ds_read_b128 v[190:193], v220 offset:7168
	s_add_u32 s26, s10, s42
	s_addc_u32 s27, s11, s43
	s_mov_b32 m0, s89
	s_nop 0
	global_load_lds_dwordx4 v215, s[26:27]
	s_mov_b32 m0, s90
	s_nop 0
	global_load_lds_dwordx4 v217, s[26:27]
	s_waitcnt vmcnt(8) lgkmcnt(0)
	s_setprio 1
	s_barrier
	v_mfma_f32_16x16x32_bf16 v[126:129], v[130:133], v[162:165], v[126:129]
	v_mfma_f32_16x16x32_bf16 v[122:125], v[138:141], v[162:165], v[122:125]
	v_mfma_f32_16x16x32_bf16 v[118:121], v[130:133], v[170:173], v[118:121]
	v_mfma_f32_16x16x32_bf16 v[114:117], v[138:141], v[170:173], v[114:117]
	v_mfma_f32_16x16x32_bf16 v[110:113], v[130:133], v[178:181], v[110:113]
	v_mfma_f32_16x16x32_bf16 v[106:109], v[138:141], v[178:181], v[106:109]
	v_mfma_f32_16x16x32_bf16 v[102:105], v[130:133], v[186:189], v[102:105]
	v_mfma_f32_16x16x32_bf16 v[98:101], v[138:141], v[186:189], v[98:101]
	v_mfma_f32_16x16x32_bf16 v[126:129], v[134:137], v[166:169], v[126:129]
	v_mfma_f32_16x16x32_bf16 v[122:125], v[142:145], v[166:169], v[122:125]
	v_mfma_f32_16x16x32_bf16 v[118:121], v[134:137], v[174:177], v[118:121]
	v_mfma_f32_16x16x32_bf16 v[114:117], v[142:145], v[174:177], v[114:117]
	v_mfma_f32_16x16x32_bf16 v[110:113], v[134:137], v[182:185], v[110:113]
	v_mfma_f32_16x16x32_bf16 v[106:109], v[142:145], v[182:185], v[106:109]
	v_mfma_f32_16x16x32_bf16 v[102:105], v[134:137], v[190:193], v[102:105]
	v_mfma_f32_16x16x32_bf16 v[98:101], v[142:145], v[190:193], v[98:101]
	v_mfma_f32_16x16x32_bf16 v[94:97], v[146:149], v[162:165], v[94:97]
	v_mfma_f32_16x16x32_bf16 v[90:93], v[154:157], v[162:165], v[90:93]
	v_mfma_f32_16x16x32_bf16 v[86:89], v[146:149], v[170:173], v[86:89]
	v_mfma_f32_16x16x32_bf16 v[82:85], v[154:157], v[170:173], v[82:85]
	v_mfma_f32_16x16x32_bf16 v[78:81], v[146:149], v[178:181], v[78:81]
	v_mfma_f32_16x16x32_bf16 v[74:77], v[154:157], v[178:181], v[74:77]
	v_mfma_f32_16x16x32_bf16 v[70:73], v[146:149], v[186:189], v[70:73]
	v_mfma_f32_16x16x32_bf16 v[66:69], v[154:157], v[186:189], v[66:69]
	v_mfma_f32_16x16x32_bf16 v[94:97], v[150:153], v[166:169], v[94:97]
	v_mfma_f32_16x16x32_bf16 v[90:93], v[158:161], v[166:169], v[90:93]
	v_mfma_f32_16x16x32_bf16 v[86:89], v[150:153], v[174:177], v[86:89]
	v_mfma_f32_16x16x32_bf16 v[82:85], v[158:161], v[174:177], v[82:85]
	v_mfma_f32_16x16x32_bf16 v[78:81], v[150:153], v[182:185], v[78:81]
	v_mfma_f32_16x16x32_bf16 v[74:77], v[158:161], v[182:185], v[74:77]
	v_mfma_f32_16x16x32_bf16 v[70:73], v[150:153], v[190:193], v[70:73]
	v_mfma_f32_16x16x32_bf16 v[66:69], v[158:161], v[190:193], v[66:69]
	s_setprio 0
	s_barrier
	ds_read_b128 v[162:165], v220 offset:16384
	ds_read_b128 v[166:169], v220 offset:17408
	ds_read_b128 v[170:173], v220 offset:18432
	ds_read_b128 v[174:177], v220 offset:19456
	ds_read_b128 v[178:181], v220 offset:20480
	ds_read_b128 v[182:185], v220 offset:21504
	ds_read_b128 v[186:189], v220 offset:22528
	ds_read_b128 v[190:193], v220 offset:23552
	s_mov_b32 m0, s70
	s_nop 0
	global_load_lds_dwordx4 v216, s[64:65]
	s_mov_b32 m0, s71
	s_nop 0
	global_load_lds_dwordx4 v218, s[64:65]
	s_add_u32 s68, s64, s20
	s_addc_u32 s69, s65, s21
	s_mov_b32 m0, s72
	s_nop 0
	global_load_lds_dwordx4 v216, s[68:69]
	s_mov_b32 m0, s73
	s_nop 0
	global_load_lds_dwordx4 v218, s[68:69]
	s_nop 0
	s_mov_b32 m0, s31
	s_nop 0
	global_load_lds_dwordx4 v215, s[66:67]
	s_mov_b32 m0, s74
	s_nop 0
	global_load_lds_dwordx4 v217, s[66:67]
	s_waitcnt vmcnt(8) lgkmcnt(0)
	s_setprio 1
	s_barrier
	v_mfma_f32_16x16x32_bf16 v[62:65], v[130:133], v[162:165], v[62:65]
	v_mfma_f32_16x16x32_bf16 v[58:61], v[138:141], v[162:165], v[58:61]
	v_mfma_f32_16x16x32_bf16 v[54:57], v[130:133], v[170:173], v[54:57]
	v_mfma_f32_16x16x32_bf16 v[50:53], v[138:141], v[170:173], v[50:53]
	v_mfma_f32_16x16x32_bf16 v[46:49], v[130:133], v[178:181], v[46:49]
	v_mfma_f32_16x16x32_bf16 v[42:45], v[138:141], v[178:181], v[42:45]
	v_mfma_f32_16x16x32_bf16 v[38:41], v[130:133], v[186:189], v[38:41]
	v_mfma_f32_16x16x32_bf16 v[34:37], v[138:141], v[186:189], v[34:37]
	v_mfma_f32_16x16x32_bf16 v[62:65], v[134:137], v[166:169], v[62:65]
	v_mfma_f32_16x16x32_bf16 v[58:61], v[142:145], v[166:169], v[58:61]
	v_mfma_f32_16x16x32_bf16 v[54:57], v[134:137], v[174:177], v[54:57]
	v_mfma_f32_16x16x32_bf16 v[50:53], v[142:145], v[174:177], v[50:53]
	v_mfma_f32_16x16x32_bf16 v[46:49], v[134:137], v[182:185], v[46:49]
	v_mfma_f32_16x16x32_bf16 v[42:45], v[142:145], v[182:185], v[42:45]
	v_mfma_f32_16x16x32_bf16 v[38:41], v[134:137], v[190:193], v[38:41]
	v_mfma_f32_16x16x32_bf16 v[34:37], v[142:145], v[190:193], v[34:37]
	v_mfma_f32_16x16x32_bf16 v[30:33], v[146:149], v[162:165], v[30:33]
	v_mfma_f32_16x16x32_bf16 v[26:29], v[154:157], v[162:165], v[26:29]
	v_mfma_f32_16x16x32_bf16 v[22:25], v[146:149], v[170:173], v[22:25]
	v_mfma_f32_16x16x32_bf16 v[18:21], v[154:157], v[170:173], v[18:21]
	v_mfma_f32_16x16x32_bf16 v[14:17], v[146:149], v[178:181], v[14:17]
	v_mfma_f32_16x16x32_bf16 v[10:13], v[154:157], v[178:181], v[10:13]
	v_mfma_f32_16x16x32_bf16 v[6:9], v[146:149], v[186:189], v[6:9]
	v_mfma_f32_16x16x32_bf16 v[2:5], v[154:157], v[186:189], v[2:5]
	v_mfma_f32_16x16x32_bf16 v[30:33], v[150:153], v[166:169], v[30:33]
	v_mfma_f32_16x16x32_bf16 v[26:29], v[158:161], v[166:169], v[26:29]
	v_mfma_f32_16x16x32_bf16 v[22:25], v[150:153], v[174:177], v[22:25]
	v_mfma_f32_16x16x32_bf16 v[18:21], v[158:161], v[174:177], v[18:21]
	v_mfma_f32_16x16x32_bf16 v[14:17], v[150:153], v[182:185], v[14:17]
	v_mfma_f32_16x16x32_bf16 v[10:13], v[158:161], v[182:185], v[10:13]
	v_mfma_f32_16x16x32_bf16 v[6:9], v[150:153], v[190:193], v[6:9]
	v_mfma_f32_16x16x32_bf16 v[2:5], v[158:161], v[190:193], v[2:5]
	s_setprio 0
	s_barrier
	v_add_u32_e32 v0, 0x18000, v219
	ds_read_b128 v[130:133], v0
	ds_read_b128 v[134:137], v0 offset:1024
	ds_read_b128 v[138:141], v0 offset:2048
	ds_read_b128 v[142:145], v0 offset:3072
	v_add_u32_e32 v0, 0x1c000, v219
	ds_read_b128 v[146:149], v0
	ds_read_b128 v[150:153], v0 offset:1024
	ds_read_b128 v[154:157], v0 offset:2048
	ds_read_b128 v[158:161], v0 offset:3072
	ds_read_b128 v[162:165], v220 offset:32768
	ds_read_b128 v[166:169], v220 offset:33792
	ds_read_b128 v[170:173], v220 offset:34816
	ds_read_b128 v[174:177], v220 offset:35840
	ds_read_b128 v[178:181], v220 offset:36864
	ds_read_b128 v[182:185], v220 offset:37888
	ds_read_b128 v[186:189], v220 offset:38912
	ds_read_b128 v[190:193], v220 offset:39936
	s_add_u32 s26, s66, s4
	s_addc_u32 s27, s67, s5
	s_mov_b32 m0, s75
	s_nop 0
	global_load_lds_dwordx4 v215, s[26:27]
	s_mov_b32 m0, s79
	s_nop 0
	global_load_lds_dwordx4 v217, s[26:27]
	s_waitcnt vmcnt(8) lgkmcnt(0)
	s_setprio 1
	s_barrier
	v_mfma_f32_16x16x32_bf16 v[126:129], v[130:133], v[162:165], v[126:129]
	v_mfma_f32_16x16x32_bf16 v[122:125], v[138:141], v[162:165], v[122:125]
	v_mfma_f32_16x16x32_bf16 v[118:121], v[130:133], v[170:173], v[118:121]
	v_mfma_f32_16x16x32_bf16 v[114:117], v[138:141], v[170:173], v[114:117]
	v_mfma_f32_16x16x32_bf16 v[110:113], v[130:133], v[178:181], v[110:113]
	v_mfma_f32_16x16x32_bf16 v[106:109], v[138:141], v[178:181], v[106:109]
	v_mfma_f32_16x16x32_bf16 v[102:105], v[130:133], v[186:189], v[102:105]
	v_mfma_f32_16x16x32_bf16 v[98:101], v[138:141], v[186:189], v[98:101]
	v_mfma_f32_16x16x32_bf16 v[126:129], v[134:137], v[166:169], v[126:129]
	v_mfma_f32_16x16x32_bf16 v[122:125], v[142:145], v[166:169], v[122:125]
	v_mfma_f32_16x16x32_bf16 v[118:121], v[134:137], v[174:177], v[118:121]
	v_mfma_f32_16x16x32_bf16 v[114:117], v[142:145], v[174:177], v[114:117]
	v_mfma_f32_16x16x32_bf16 v[110:113], v[134:137], v[182:185], v[110:113]
	v_mfma_f32_16x16x32_bf16 v[106:109], v[142:145], v[182:185], v[106:109]
	v_mfma_f32_16x16x32_bf16 v[102:105], v[134:137], v[190:193], v[102:105]
	v_mfma_f32_16x16x32_bf16 v[98:101], v[142:145], v[190:193], v[98:101]
	v_mfma_f32_16x16x32_bf16 v[94:97], v[146:149], v[162:165], v[94:97]
	v_mfma_f32_16x16x32_bf16 v[90:93], v[154:157], v[162:165], v[90:93]
	v_mfma_f32_16x16x32_bf16 v[86:89], v[146:149], v[170:173], v[86:89]
	v_mfma_f32_16x16x32_bf16 v[82:85], v[154:157], v[170:173], v[82:85]
	v_mfma_f32_16x16x32_bf16 v[78:81], v[146:149], v[178:181], v[78:81]
	v_mfma_f32_16x16x32_bf16 v[74:77], v[154:157], v[178:181], v[74:77]
	v_mfma_f32_16x16x32_bf16 v[70:73], v[146:149], v[186:189], v[70:73]
	v_mfma_f32_16x16x32_bf16 v[66:69], v[154:157], v[186:189], v[66:69]
	v_mfma_f32_16x16x32_bf16 v[94:97], v[150:153], v[166:169], v[94:97]
	v_mfma_f32_16x16x32_bf16 v[90:93], v[158:161], v[166:169], v[90:93]
	v_mfma_f32_16x16x32_bf16 v[86:89], v[150:153], v[174:177], v[86:89]
	v_mfma_f32_16x16x32_bf16 v[82:85], v[158:161], v[174:177], v[82:85]
	v_mfma_f32_16x16x32_bf16 v[78:81], v[150:153], v[182:185], v[78:81]
	v_mfma_f32_16x16x32_bf16 v[74:77], v[158:161], v[182:185], v[74:77]
	v_mfma_f32_16x16x32_bf16 v[70:73], v[150:153], v[190:193], v[70:73]
	v_mfma_f32_16x16x32_bf16 v[66:69], v[158:161], v[190:193], v[66:69]
	s_setprio 0
	s_barrier
	ds_read_b128 v[162:165], v220 offset:49152
	ds_read_b128 v[166:169], v220 offset:50176
	ds_read_b128 v[170:173], v220 offset:51200
	ds_read_b128 v[174:177], v220 offset:52224
	ds_read_b128 v[178:181], v220 offset:53248
	ds_read_b128 v[182:185], v220 offset:54272
	ds_read_b128 v[186:189], v220 offset:55296
	ds_read_b128 v[190:193], v220 offset:56320
	s_add_u32 s26, s64, 0x80
	s_addc_u32 s27, s65, 0
	s_mov_b32 m0, s83
	s_nop 0
	global_load_lds_dwordx4 v216, s[26:27]
	s_mov_b32 m0, s84
	s_nop 0
	global_load_lds_dwordx4 v218, s[26:27]
	s_add_u32 s26, s68, 0x80
	s_addc_u32 s27, s69, 0
	s_mov_b32 m0, s87
	s_nop 0
	global_load_lds_dwordx4 v216, s[26:27]
	s_mov_b32 m0, s88
	s_nop 0
	global_load_lds_dwordx4 v218, s[26:27]
	s_mov_b32 m0, s85
	s_nop 0
	global_load_lds_dwordx4 v215, s[62:63]
	s_mov_b32 m0, s86
	s_nop 0
	global_load_lds_dwordx4 v217, s[62:63]
	s_waitcnt vmcnt(8) lgkmcnt(0)
	s_setprio 1
	s_barrier
	v_mfma_f32_16x16x32_bf16 v[62:65], v[130:133], v[162:165], v[62:65]
	v_mfma_f32_16x16x32_bf16 v[58:61], v[138:141], v[162:165], v[58:61]
	v_mfma_f32_16x16x32_bf16 v[54:57], v[130:133], v[170:173], v[54:57]
	v_mfma_f32_16x16x32_bf16 v[50:53], v[138:141], v[170:173], v[50:53]
	v_mfma_f32_16x16x32_bf16 v[46:49], v[130:133], v[178:181], v[46:49]
	v_mfma_f32_16x16x32_bf16 v[42:45], v[138:141], v[178:181], v[42:45]
	v_mfma_f32_16x16x32_bf16 v[38:41], v[130:133], v[186:189], v[38:41]
	v_mfma_f32_16x16x32_bf16 v[34:37], v[138:141], v[186:189], v[34:37]
	v_mfma_f32_16x16x32_bf16 v[62:65], v[134:137], v[166:169], v[62:65]
	v_mfma_f32_16x16x32_bf16 v[58:61], v[142:145], v[166:169], v[58:61]
	v_mfma_f32_16x16x32_bf16 v[54:57], v[134:137], v[174:177], v[54:57]
	v_mfma_f32_16x16x32_bf16 v[50:53], v[142:145], v[174:177], v[50:53]
	v_mfma_f32_16x16x32_bf16 v[46:49], v[134:137], v[182:185], v[46:49]
	v_mfma_f32_16x16x32_bf16 v[42:45], v[142:145], v[182:185], v[42:45]
	v_mfma_f32_16x16x32_bf16 v[38:41], v[134:137], v[190:193], v[38:41]
	v_mfma_f32_16x16x32_bf16 v[34:37], v[142:145], v[190:193], v[34:37]
	v_mfma_f32_16x16x32_bf16 v[30:33], v[146:149], v[162:165], v[30:33]
	v_mfma_f32_16x16x32_bf16 v[26:29], v[154:157], v[162:165], v[26:29]
	v_mfma_f32_16x16x32_bf16 v[22:25], v[146:149], v[170:173], v[22:25]
	v_mfma_f32_16x16x32_bf16 v[18:21], v[154:157], v[170:173], v[18:21]
	v_mfma_f32_16x16x32_bf16 v[14:17], v[146:149], v[178:181], v[14:17]
	v_mfma_f32_16x16x32_bf16 v[10:13], v[154:157], v[178:181], v[10:13]
	v_mfma_f32_16x16x32_bf16 v[6:9], v[146:149], v[186:189], v[6:9]
	v_mfma_f32_16x16x32_bf16 v[2:5], v[154:157], v[186:189], v[2:5]
	v_mfma_f32_16x16x32_bf16 v[30:33], v[150:153], v[166:169], v[30:33]
	v_mfma_f32_16x16x32_bf16 v[26:29], v[158:161], v[166:169], v[26:29]
	v_mfma_f32_16x16x32_bf16 v[22:25], v[150:153], v[174:177], v[22:25]
	v_mfma_f32_16x16x32_bf16 v[18:21], v[158:161], v[174:177], v[18:21]
	v_mfma_f32_16x16x32_bf16 v[14:17], v[150:153], v[182:185], v[14:17]
	v_mfma_f32_16x16x32_bf16 v[10:13], v[158:161], v[182:185], v[10:13]
	v_mfma_f32_16x16x32_bf16 v[6:9], v[150:153], v[190:193], v[6:9]
	v_mfma_f32_16x16x32_bf16 v[2:5], v[158:161], v[190:193], v[2:5]
	s_setprio 0
	s_barrier
	s_add_i32 s25, s25, 2
	s_add_u32 s42, s42, 0x100
	s_addc_u32 s43, s43, 0
	s_cmp_gt_u32 s25, 41
	s_cbranch_scc0 .LBB0_645
	s_and_b64 vcc, exec, s[50:51]
	s_cbranch_vccz .LBB0_648
	s_barrier
